# edgehoist: K-loop back-edge bookkeeping (counter/offset adds, address advances) moved from after the last segment barrier into the MFMA shadow of the last MFMA block, in all 6 live GEMM K-loops
# speedup vs baseline: 1.0108x; 1.0108x over previous
;     __host__ __device__ bool next(int i, Unit& u) const { return at((long)i * G + c, u); }
;     __host__ __device__ bool next(int i, Unit& u) const { if (i != 0 || c >= cnt) return false; u.pm = pm0 + c / nN; u.pn = c % nN; u.k0 = 0; u.nt = ntk; return true; }
; #define PG8_STAGE(bufoff, gbase, voff) do { _Pragma("unroll") for (int _i = 0; _i < 2; ++_i) \
;         __builtin_amdgcn_global_load_lds((const unsigned*)((const char*)(gbase) + (voff)[_i]), (PG8_LAS unsigned*)(lds + (bufoff) + ldsw + _i * 8192), 16, 0, 0); } while (0)
; #define PG8_BAR __builtin_amdgcn_s_barrier()
;     ...
;     for (;;) {
;         const bool has_next = S.next(ui + 1, nxt);
;         const char* nA = has_next ? (const char*)g.A + (size_t)nxt.pm * tstep + (size_t)nxt.k0 * (BK * 2) : cA; const char* nB = has_next ? (const char*)g.Bt + (size_t)nxt.pn * tstep + (size_t)nxt.k0 * (BK * 2) : cB;
;         const int nt = cur.nt;
;         for (int t = 0; t < nt; t += 2) {
;             const bool last = (t == nt - 2);
;             const char* a1 = cA + (size_t)(t + 1) * kstep;
;             const char* a2 = last ? nA : cA + (size_t)(t + 2) * kstep; const char* b2 = last ? nB : cB + (size_t)(t + 2) * kstep;
;             const char* a3 = a2 + kstep; const char* b3 = b2 + kstep;
;             if (last && has_next) S.a_ready(nxt);
;             if constexpr (SP2) {
;             PG8_LDB(B0, 0, 0); PG8_LDB(B1, 0, 1); PG8_SCHED; PG8_LDA(At, 0, 0); PG8_STAGEA(PG8_SA(1, 1), a1 + hstep, voffA);
;             PG8_WAIT_V(8); PG8_WAIT_L(0); PG8_BAR; PG8_MMA(0, 0, At, B0); PG8_MMA(0, 1, At, B1); PG8_BAR; PG8_SCHED;
;             PG8_LDA(At, 0, 1); PG8_STAGE(PG8_SB(0, 0), b2, voffB); PG8_STAGE(PG8_SB(0, 1), b2 + hstepB, voffB); PG8_STAGEA(PG8_SA(0, 0), a2, voffA);
;             PG8_WAIT_V(8); PG8_WAIT_L(0); PG8_BAR; PG8_MMA(1, 0, At, B0); PG8_MMA(1, 1, At, B1); PG8_BAR; PG8_SCHED;
;             PG8_LDB(B0, 1, 0); PG8_LDB(B1, 1, 1); PG8_SCHED; PG8_LDA(At, 1, 0); PG8_STAGEA(PG8_SA(0, 1), a2 + hstep, voffA);
;             PG8_WAIT_V(8); PG8_WAIT_L(0); PG8_BAR; PG8_MMA(0, 0, At, B0); PG8_MMA(0, 1, At, B1); PG8_BAR; PG8_SCHED;
;             PG8_LDA(At, 1, 1); PG8_STAGE(PG8_SB(1, 0), b3, voffB); PG8_STAGE(PG8_SB(1, 1), b3 + hstepB, voffB); PG8_STAGEA(PG8_SA(1, 0), a3, voffA);
;             PG8_WAIT_V(8); PG8_WAIT_L(0); PG8_BAR; PG8_MMA(1, 0, At, B0); PG8_MMA(1, 1, At, B1); PG8_BAR; PG8_SCHED;
.Lsprio_0:
.LBB0_119:
	ds_read_b128 v[128:131], v229
	ds_read_b128 v[132:135], v229 offset:1024
	ds_read_b128 v[136:139], v229 offset:2048
	ds_read_b128 v[140:143], v229 offset:3072
	ds_read_b128 v[176:179], v230
	ds_read_b128 v[180:183], v230 offset:1024
	ds_read_b128 v[184:187], v230 offset:2048
	ds_read_b128 v[188:191], v230 offset:3072
	s_add_u32 s36, s8, 0xfffc0080
	s_addc_u32 s37, s9, -1
	s_cmp_eq_u32 s78, 12
	s_cselect_b32 s39, s5, s37
	s_cselect_b32 s38, s7, s36
	s_cselect_b32 s37, s27, s59
	s_cselect_b32 s36, s29, s58
	v_lshl_add_u64 v[172:173], s[8:9], 0, v[164:165]
	s_add_i32 m0, s85, 0xc000
	ds_read_b128 v[192:195], v231
	ds_read_b128 v[196:199], v231 offset:1024
	ds_read_b128 v[238:241], v231 offset:2048
	ds_read_b128 v[242:245], v231 offset:3072
	ds_read_b128 v[246:249], v231 offset:4096
	ds_read_b128 v[250:253], v231 offset:5120
	ds_read_b128 v[210:213], v231 offset:6144
	ds_read_b128 v[214:217], v231 offset:7168
	global_load_lds_dwordx4 v[172:173], off
	v_lshl_add_u64 v[172:173], s[8:9], 0, v[166:167]
	s_add_i32 m0, s85, 0xe000
	s_nop 0
	global_load_lds_dwordx4 v[172:173], off
	s_waitcnt vmcnt(8)
	s_waitcnt lgkmcnt(0)
	s_barrier
	v_mfma_f32_16x16x32_bf16 v[76:79], v[128:131], v[192:195], v[76:79]
	v_mfma_f32_16x16x32_bf16 v[72:75], v[136:139], v[192:195], v[72:75]
	v_mfma_f32_16x16x32_bf16 v[124:127], v[128:131], v[238:241], v[124:127]
	v_mfma_f32_16x16x32_bf16 v[120:123], v[136:139], v[238:241], v[120:123]
	v_mfma_f32_16x16x32_bf16 v[108:111], v[128:131], v[246:249], v[108:111]
	v_mfma_f32_16x16x32_bf16 v[104:107], v[136:139], v[246:249], v[104:107]
	v_mfma_f32_16x16x32_bf16 v[92:95], v[128:131], v[210:213], v[92:95]
	v_mfma_f32_16x16x32_bf16 v[88:91], v[136:139], v[210:213], v[88:91]
	v_mfma_f32_16x16x32_bf16 v[76:79], v[132:135], v[196:199], v[76:79]
	v_mfma_f32_16x16x32_bf16 v[72:75], v[140:143], v[196:199], v[72:75]
	v_mfma_f32_16x16x32_bf16 v[124:127], v[132:135], v[242:245], v[124:127]
	v_mfma_f32_16x16x32_bf16 v[120:123], v[140:143], v[242:245], v[120:123]
	v_mfma_f32_16x16x32_bf16 v[108:111], v[132:135], v[250:253], v[108:111]
	v_mfma_f32_16x16x32_bf16 v[104:107], v[140:143], v[250:253], v[104:107]
	v_mfma_f32_16x16x32_bf16 v[92:95], v[132:135], v[214:217], v[92:95]
	v_mfma_f32_16x16x32_bf16 v[88:91], v[140:143], v[214:217], v[88:91]
	v_mfma_f32_16x16x32_bf16 v[52:55], v[176:179], v[192:195], v[52:55]
	v_mfma_f32_16x16x32_bf16 v[48:51], v[184:187], v[192:195], v[48:51]
	v_mfma_f32_16x16x32_bf16 v[116:119], v[176:179], v[238:241], v[116:119]
	v_mfma_f32_16x16x32_bf16 v[112:115], v[184:187], v[238:241], v[112:115]
	v_mfma_f32_16x16x32_bf16 v[100:103], v[176:179], v[246:249], v[100:103]
	v_mfma_f32_16x16x32_bf16 v[96:99], v[184:187], v[246:249], v[96:99]
	v_mfma_f32_16x16x32_bf16 v[84:87], v[176:179], v[210:213], v[84:87]
	v_mfma_f32_16x16x32_bf16 v[80:83], v[184:187], v[210:213], v[80:83]
	v_mfma_f32_16x16x32_bf16 v[52:55], v[180:183], v[196:199], v[52:55]
	v_mfma_f32_16x16x32_bf16 v[48:51], v[188:191], v[196:199], v[48:51]
	v_mfma_f32_16x16x32_bf16 v[116:119], v[180:183], v[242:245], v[116:119]
	v_mfma_f32_16x16x32_bf16 v[112:115], v[188:191], v[242:245], v[112:115]
	v_mfma_f32_16x16x32_bf16 v[100:103], v[180:183], v[250:253], v[100:103]
	v_mfma_f32_16x16x32_bf16 v[96:99], v[188:191], v[250:253], v[96:99]
	v_mfma_f32_16x16x32_bf16 v[84:87], v[180:183], v[214:217], v[84:87]
	v_mfma_f32_16x16x32_bf16 v[80:83], v[188:191], v[214:217], v[80:83]
	s_barrier
	s_add_i32 s79, s73, s67
	v_lshl_add_u64 v[172:173], s[36:37], 0, v[146:147]
	s_mov_b32 m0, s79
	ds_read_b128 v[192:195], v231 offset:16384
	ds_read_b128 v[196:199], v231 offset:17408
	ds_read_b128 v[210:213], v231 offset:18432
	ds_read_b128 v[214:217], v231 offset:19456
	ds_read_b128 v[238:241], v231 offset:20480
	ds_read_b128 v[242:245], v231 offset:21504
	ds_read_b128 v[246:249], v231 offset:22528
	ds_read_b128 v[250:253], v231 offset:23552
	global_load_lds_dwordx4 v[172:173], off
	s_add_i32 m0, s79, 0x2000
	s_add_u32 s80, s36, 0x10000
	v_lshl_add_u64 v[202:203], s[36:37], 0, v[150:151]
	s_addc_u32 s81, s37, 0
	s_add_i32 s79, s46, s67
	global_load_lds_dwordx4 v[202:203], off
	v_lshl_add_u64 v[204:205], s[80:81], 0, v[146:147]
	s_mov_b32 m0, s79
	v_lshl_add_u64 v[206:207], s[38:39], 0, v[148:149]
	global_load_lds_dwordx4 v[204:205], off
	v_lshl_add_u64 v[204:205], s[80:81], 0, v[150:151]
	s_add_i32 m0, s79, 0x2000
	s_nop 0
	global_load_lds_dwordx4 v[204:205], off
	v_lshl_add_u64 v[204:205], s[38:39], 0, v[144:145]
	s_mov_b32 m0, s85
	s_nop 0
	global_load_lds_dwordx4 v[204:205], off
	s_mov_b32 m0, s86
	s_nop 0
	global_load_lds_dwordx4 v[206:207], off
	s_waitcnt vmcnt(8)
	s_waitcnt lgkmcnt(0)
	s_barrier
; #define PG8_STAGE(bufoff, gbase, voff) do { _Pragma("unroll") for (int _i = 0; _i < 2; ++_i) \
;         __builtin_amdgcn_global_load_lds((const unsigned*)((const char*)(gbase) + (voff)[_i]), (PG8_LAS unsigned*)(lds + (bufoff) + ldsw + _i * 8192), 16, 0, 0); } while (0)
; #define PG8_STAGEA(bufoff, gbase, voff) do { _Pragma("unroll") for (int _i = 0; _i < 2; ++_i) \
;         __builtin_amdgcn_global_load_lds((const unsigned*)((const char*)(gbase) + (voff)[_i]), (PG8_LAS unsigned*)(lds + (bufoff) + ldsw + _i * 8192), 16, 0, AUXA); } while (0)
; #define PG8_LDA(dst, b, h) do { _Pragma("unroll") for (int m = 0; m < 4; ++m) _Pragma("unroll") for (int k = 0; k < 2; ++k) dst[m][k] = *(const PG8_LAS bf16x8*)(lds + PG8_SA(b, h) + aoff + m * 2048 + k * 1024); } while (0)
; #define PG8_LDB(dst, b, h) do { _Pragma("unroll") for (int n = 0; n < 2; ++n) _Pragma("unroll") for (int k = 0; k < 2; ++k) dst[n][k] = *(const PG8_LAS bf16x8*)(lds + PG8_SB(b, h) + boff + n * 2048 + k * 1024); } while (0)
; #define PG8_WAIT_V(n) asm volatile("s_waitcnt vmcnt(" #n ")" ::: "memory")
; #define PG8_WAIT_L(n) asm volatile("s_waitcnt lgkmcnt(" #n ")" ::: "memory")
; #define PG8_BAR __builtin_amdgcn_s_barrier()
; #define PG8_SCHED __builtin_amdgcn_sched_barrier(0)
;     ...
;             if constexpr (SP2) {
;             PG8_LDB(B0, 0, 0); PG8_LDB(B1, 0, 1); PG8_SCHED; PG8_LDA(At, 0, 0); PG8_STAGEA(PG8_SA(1, 1), a1 + hstep, voffA);
;             PG8_WAIT_V(8); PG8_WAIT_L(0); PG8_BAR; PG8_MMA(0, 0, At, B0); PG8_MMA(0, 1, At, B1); PG8_BAR; PG8_SCHED;
;             PG8_LDA(At, 0, 1); PG8_STAGE(PG8_SB(0, 0), b2, voffB); PG8_STAGE(PG8_SB(0, 1), b2 + hstepB, voffB); PG8_STAGEA(PG8_SA(0, 0), a2, voffA);
;             PG8_WAIT_V(8); PG8_WAIT_L(0); PG8_BAR; PG8_MMA(1, 0, At, B0); PG8_MMA(1, 1, At, B1); PG8_BAR; PG8_SCHED;
;             PG8_LDB(B0, 1, 0); PG8_LDB(B1, 1, 1); PG8_SCHED; PG8_LDA(At, 1, 0); PG8_STAGEA(PG8_SA(0, 1), a2 + hstep, voffA);
;             PG8_WAIT_V(8); PG8_WAIT_L(0); PG8_BAR; PG8_MMA(0, 0, At, B0); PG8_MMA(0, 1, At, B1); PG8_BAR; PG8_SCHED;
;             PG8_LDA(At, 1, 1); PG8_STAGE(PG8_SB(1, 0), b3, voffB); PG8_STAGE(PG8_SB(1, 1), b3 + hstepB, voffB); PG8_STAGEA(PG8_SA(1, 0), a3, voffA);
;             PG8_WAIT_V(8); PG8_WAIT_L(0); PG8_BAR; PG8_MMA(1, 0, At, B0); PG8_MMA(1, 1, At, B1); PG8_BAR; PG8_SCHED;
	v_mfma_f32_16x16x32_bf16 v[68:71], v[128:131], v[192:195], v[68:71]
	v_mfma_f32_16x16x32_bf16 v[64:67], v[136:139], v[192:195], v[64:67]
	v_mfma_f32_16x16x32_bf16 v[44:47], v[128:131], v[210:213], v[44:47]
	v_mfma_f32_16x16x32_bf16 v[40:43], v[136:139], v[210:213], v[40:43]
	v_mfma_f32_16x16x32_bf16 v[28:31], v[128:131], v[238:241], v[28:31]
	v_mfma_f32_16x16x32_bf16 v[24:27], v[136:139], v[238:241], v[24:27]
	v_mfma_f32_16x16x32_bf16 v[12:15], v[128:131], v[246:249], v[12:15]
	v_mfma_f32_16x16x32_bf16 v[8:11], v[136:139], v[246:249], v[8:11]
	v_mfma_f32_16x16x32_bf16 v[68:71], v[132:135], v[196:199], v[68:71]
	v_mfma_f32_16x16x32_bf16 v[64:67], v[140:143], v[196:199], v[64:67]
	v_mfma_f32_16x16x32_bf16 v[44:47], v[132:135], v[214:217], v[44:47]
	v_mfma_f32_16x16x32_bf16 v[40:43], v[140:143], v[214:217], v[40:43]
	v_mfma_f32_16x16x32_bf16 v[28:31], v[132:135], v[242:245], v[28:31]
	v_mfma_f32_16x16x32_bf16 v[24:27], v[140:143], v[242:245], v[24:27]
	v_mfma_f32_16x16x32_bf16 v[12:15], v[132:135], v[250:253], v[12:15]
	v_mfma_f32_16x16x32_bf16 v[8:11], v[140:143], v[250:253], v[8:11]
	v_mfma_f32_16x16x32_bf16 v[60:63], v[176:179], v[192:195], v[60:63]
	v_mfma_f32_16x16x32_bf16 v[56:59], v[184:187], v[192:195], v[56:59]
	v_mfma_f32_16x16x32_bf16 v[36:39], v[176:179], v[210:213], v[36:39]
	v_mfma_f32_16x16x32_bf16 v[32:35], v[184:187], v[210:213], v[32:35]
	v_mfma_f32_16x16x32_bf16 v[20:23], v[176:179], v[238:241], v[20:23]
	v_mfma_f32_16x16x32_bf16 v[16:19], v[184:187], v[238:241], v[16:19]
	v_mfma_f32_16x16x32_bf16 v[4:7], v[176:179], v[246:249], v[4:7]
	v_mfma_f32_16x16x32_bf16 v[0:3], v[184:187], v[246:249], v[0:3]
	v_mfma_f32_16x16x32_bf16 v[60:63], v[180:183], v[196:199], v[60:63]
	v_mfma_f32_16x16x32_bf16 v[56:59], v[188:191], v[196:199], v[56:59]
	v_mfma_f32_16x16x32_bf16 v[36:39], v[180:183], v[214:217], v[36:39]
	v_mfma_f32_16x16x32_bf16 v[32:35], v[188:191], v[214:217], v[32:35]
	v_mfma_f32_16x16x32_bf16 v[20:23], v[180:183], v[242:245], v[20:23]
	v_mfma_f32_16x16x32_bf16 v[16:19], v[188:191], v[242:245], v[16:19]
	v_mfma_f32_16x16x32_bf16 v[4:7], v[180:183], v[250:253], v[4:7]
	v_mfma_f32_16x16x32_bf16 v[0:3], v[188:191], v[250:253], v[0:3]
	s_barrier
	s_add_i32 s79, 0, 0x18000
	s_add_i32 s80, 0, 0x1c000
	v_add_u32_e32 v140, s79, v226
	v_add_u32_e32 v152, s80, v226
	ds_read_b128 v[128:131], v140
	ds_read_b128 v[132:135], v140 offset:1024
	ds_read_b128 v[136:139], v140 offset:2048
	ds_read_b128 v[140:143], v140 offset:3072
	ds_read_b128 v[176:179], v152
	ds_read_b128 v[180:183], v152 offset:1024
	ds_read_b128 v[184:187], v152 offset:2048
	ds_read_b128 v[188:191], v152 offset:3072
	s_add_u32 s38, s38, 0x40000
	s_addc_u32 s39, s39, 0
	s_mov_b32 m0, s87
	v_lshl_add_u64 v[218:219], s[38:39], 0, v[144:145]
	ds_read_b128 v[192:195], v231 offset:32768
	ds_read_b128 v[196:199], v231 offset:33792
	ds_read_b128 v[210:213], v231 offset:34816
	ds_read_b128 v[214:217], v231 offset:35840
	ds_read_b128 v[238:241], v231 offset:36864
	ds_read_b128 v[242:245], v231 offset:37888
	ds_read_b128 v[246:249], v231 offset:38912
	ds_read_b128 v[250:253], v231 offset:39936
	global_load_lds_dwordx4 v[218:219], off
	v_lshl_add_u64 v[218:219], s[38:39], 0, v[148:149]
	s_mov_b32 m0, s88
	s_nop 0
	global_load_lds_dwordx4 v[218:219], off
	s_waitcnt vmcnt(8)
	s_waitcnt lgkmcnt(0)
	s_barrier
	v_mfma_f32_16x16x32_bf16 v[76:79], v[128:131], v[192:195], v[76:79]
	v_mfma_f32_16x16x32_bf16 v[72:75], v[136:139], v[192:195], v[72:75]
	v_mfma_f32_16x16x32_bf16 v[124:127], v[128:131], v[210:213], v[124:127]
	v_mfma_f32_16x16x32_bf16 v[120:123], v[136:139], v[210:213], v[120:123]
	v_mfma_f32_16x16x32_bf16 v[108:111], v[128:131], v[238:241], v[108:111]
	v_mfma_f32_16x16x32_bf16 v[104:107], v[136:139], v[238:241], v[104:107]
	v_mfma_f32_16x16x32_bf16 v[92:95], v[128:131], v[246:249], v[92:95]
	v_mfma_f32_16x16x32_bf16 v[88:91], v[136:139], v[246:249], v[88:91]
	v_mfma_f32_16x16x32_bf16 v[76:79], v[132:135], v[196:199], v[76:79]
	v_mfma_f32_16x16x32_bf16 v[72:75], v[140:143], v[196:199], v[72:75]
	v_mfma_f32_16x16x32_bf16 v[124:127], v[132:135], v[214:217], v[124:127]
	v_mfma_f32_16x16x32_bf16 v[120:123], v[140:143], v[214:217], v[120:123]
	v_mfma_f32_16x16x32_bf16 v[108:111], v[132:135], v[242:245], v[108:111]
	v_mfma_f32_16x16x32_bf16 v[104:107], v[140:143], v[242:245], v[104:107]
	v_mfma_f32_16x16x32_bf16 v[92:95], v[132:135], v[250:253], v[92:95]
	v_mfma_f32_16x16x32_bf16 v[88:91], v[140:143], v[250:253], v[88:91]
	v_mfma_f32_16x16x32_bf16 v[52:55], v[176:179], v[192:195], v[52:55]
	v_mfma_f32_16x16x32_bf16 v[48:51], v[184:187], v[192:195], v[48:51]
	v_mfma_f32_16x16x32_bf16 v[116:119], v[176:179], v[210:213], v[116:119]
	v_mfma_f32_16x16x32_bf16 v[112:115], v[184:187], v[210:213], v[112:115]
	v_mfma_f32_16x16x32_bf16 v[100:103], v[176:179], v[238:241], v[100:103]
	v_mfma_f32_16x16x32_bf16 v[96:99], v[184:187], v[238:241], v[96:99]
	v_mfma_f32_16x16x32_bf16 v[84:87], v[176:179], v[246:249], v[84:87]
	v_mfma_f32_16x16x32_bf16 v[80:83], v[184:187], v[246:249], v[80:83]
	v_mfma_f32_16x16x32_bf16 v[52:55], v[180:183], v[196:199], v[52:55]
	v_mfma_f32_16x16x32_bf16 v[48:51], v[188:191], v[196:199], v[48:51]
	v_mfma_f32_16x16x32_bf16 v[116:119], v[180:183], v[214:217], v[116:119]
	v_mfma_f32_16x16x32_bf16 v[112:115], v[188:191], v[214:217], v[112:115]
	v_mfma_f32_16x16x32_bf16 v[100:103], v[180:183], v[242:245], v[100:103]
	v_mfma_f32_16x16x32_bf16 v[96:99], v[188:191], v[242:245], v[96:99]
	v_mfma_f32_16x16x32_bf16 v[84:87], v[180:183], v[250:253], v[84:87]
	v_mfma_f32_16x16x32_bf16 v[80:83], v[188:191], v[250:253], v[80:83]
	s_barrier
; #define PG8_STAGE(bufoff, gbase, voff) do { _Pragma("unroll") for (int _i = 0; _i < 2; ++_i) \
;         __builtin_amdgcn_global_load_lds((const unsigned*)((const char*)(gbase) + (voff)[_i]), (PG8_LAS unsigned*)(lds + (bufoff) + ldsw + _i * 8192), 16, 0, 0); } while (0)
; #define PG8_STAGEA(bufoff, gbase, voff) do { _Pragma("unroll") for (int _i = 0; _i < 2; ++_i) \
;         __builtin_amdgcn_global_load_lds((const unsigned*)((const char*)(gbase) + (voff)[_i]), (PG8_LAS unsigned*)(lds + (bufoff) + ldsw + _i * 8192), 16, 0, AUXA); } while (0)
; #define PG8_LDA(dst, b, h) do { _Pragma("unroll") for (int m = 0; m < 4; ++m) _Pragma("unroll") for (int k = 0; k < 2; ++k) dst[m][k] = *(const PG8_LAS bf16x8*)(lds + PG8_SA(b, h) + aoff + m * 2048 + k * 1024); } while (0)
; #define PG8_LDB(dst, b, h) do { _Pragma("unroll") for (int n = 0; n < 2; ++n) _Pragma("unroll") for (int k = 0; k < 2; ++k) dst[n][k] = *(const PG8_LAS bf16x8*)(lds + PG8_SB(b, h) + boff + n * 2048 + k * 1024); } while (0)
; #define PG8_WAIT_V(n) asm volatile("s_waitcnt vmcnt(" #n ")" ::: "memory")
; #define PG8_WAIT_L(n) asm volatile("s_waitcnt lgkmcnt(" #n ")" ::: "memory")
; #define PG8_BAR __builtin_amdgcn_s_barrier()
; #define PG8_SCHED __builtin_amdgcn_sched_barrier(0)
;     ...
;             if constexpr (SP2) {
;             PG8_LDB(B0, 0, 0); PG8_LDB(B1, 0, 1); PG8_SCHED; PG8_LDA(At, 0, 0); PG8_STAGEA(PG8_SA(1, 1), a1 + hstep, voffA);
;             PG8_WAIT_V(8); PG8_WAIT_L(0); PG8_BAR; PG8_MMA(0, 0, At, B0); PG8_MMA(0, 1, At, B1); PG8_BAR; PG8_SCHED;
;             PG8_LDA(At, 0, 1); PG8_STAGE(PG8_SB(0, 0), b2, voffB); PG8_STAGE(PG8_SB(0, 1), b2 + hstepB, voffB); PG8_STAGEA(PG8_SA(0, 0), a2, voffA);
;             PG8_WAIT_V(8); PG8_WAIT_L(0); PG8_BAR; PG8_MMA(1, 0, At, B0); PG8_MMA(1, 1, At, B1); PG8_BAR; PG8_SCHED;
;             PG8_LDB(B0, 1, 0); PG8_LDB(B1, 1, 1); PG8_SCHED; PG8_LDA(At, 1, 0); PG8_STAGEA(PG8_SA(0, 1), a2 + hstep, voffA);
;             PG8_WAIT_V(8); PG8_WAIT_L(0); PG8_BAR; PG8_MMA(0, 0, At, B0); PG8_MMA(0, 1, At, B1); PG8_BAR; PG8_SCHED;
;             PG8_LDA(At, 1, 1); PG8_STAGE(PG8_SB(1, 0), b3, voffB); PG8_STAGE(PG8_SB(1, 1), b3 + hstepB, voffB); PG8_STAGEA(PG8_SA(1, 0), a3, voffA);
;             PG8_WAIT_V(8); PG8_WAIT_L(0); PG8_BAR; PG8_MMA(1, 0, At, B0); PG8_MMA(1, 1, At, B1); PG8_BAR; PG8_SCHED;
	s_add_i32 s38, s79, s67
	v_lshl_add_u64 v[172:173], v[172:173], 0, s[16:17]
	s_mov_b32 m0, s38
	ds_read_b128 v[192:195], v231 offset:49152
	ds_read_b128 v[196:199], v231 offset:50176
	ds_read_b128 v[210:213], v231 offset:51200
	ds_read_b128 v[214:217], v231 offset:52224
	ds_read_b128 v[238:241], v231 offset:53248
	ds_read_b128 v[242:245], v231 offset:54272
	ds_read_b128 v[246:249], v231 offset:55296
	ds_read_b128 v[250:253], v231 offset:56320
	global_load_lds_dwordx4 v[172:173], off
	s_add_i32 m0, s38, 0x2000
	s_add_u32 s36, s36, 0x10080
	v_lshl_add_u64 v[172:173], v[202:203], 0, s[16:17]
	s_addc_u32 s37, s37, 0
	s_add_i32 s38, s80, s67
	global_load_lds_dwordx4 v[172:173], off
	v_lshl_add_u64 v[172:173], s[36:37], 0, v[146:147]
	s_mov_b32 m0, s38
	s_nop 0
	global_load_lds_dwordx4 v[172:173], off
	v_lshl_add_u64 v[172:173], s[36:37], 0, v[150:151]
	s_add_i32 m0, s38, 0x2000
	s_nop 0
	global_load_lds_dwordx4 v[172:173], off
	v_lshl_add_u64 v[172:173], v[204:205], 0, s[16:17]
	s_mov_b32 m0, s89
	s_nop 0
	global_load_lds_dwordx4 v[172:173], off
	v_lshl_add_u64 v[172:173], v[206:207], 0, s[16:17]
	s_mov_b32 m0, s90
	s_nop 0
	global_load_lds_dwordx4 v[172:173], off
	s_waitcnt vmcnt(8)
	s_waitcnt lgkmcnt(0)
	s_barrier
	v_mfma_f32_16x16x32_bf16 v[68:71], v[128:131], v[192:195], v[68:71]
	v_mfma_f32_16x16x32_bf16 v[64:67], v[136:139], v[192:195], v[64:67]
	v_mfma_f32_16x16x32_bf16 v[44:47], v[128:131], v[210:213], v[44:47]
	s_add_i32 s78, s78, 2
	v_mfma_f32_16x16x32_bf16 v[40:43], v[136:139], v[210:213], v[40:43]
	v_mfma_f32_16x16x32_bf16 v[28:31], v[128:131], v[238:241], v[28:31]
	s_add_u32 s8, s8, 0x100
	v_mfma_f32_16x16x32_bf16 v[24:27], v[136:139], v[238:241], v[24:27]
	v_mfma_f32_16x16x32_bf16 v[12:15], v[128:131], v[246:249], v[12:15]
	s_addc_u32 s9, s9, 0
	v_mfma_f32_16x16x32_bf16 v[8:11], v[136:139], v[246:249], v[8:11]
	v_mfma_f32_16x16x32_bf16 v[68:71], v[132:135], v[196:199], v[68:71]
	s_add_u32 s58, s58, 0x100
	v_mfma_f32_16x16x32_bf16 v[64:67], v[140:143], v[196:199], v[64:67]
	v_mfma_f32_16x16x32_bf16 v[44:47], v[132:135], v[214:217], v[44:47]
	s_addc_u32 s59, s59, 0
	v_mfma_f32_16x16x32_bf16 v[40:43], v[140:143], v[214:217], v[40:43]
	v_mfma_f32_16x16x32_bf16 v[28:31], v[132:135], v[242:245], v[28:31]
	v_mfma_f32_16x16x32_bf16 v[24:27], v[140:143], v[242:245], v[24:27]
	v_mfma_f32_16x16x32_bf16 v[12:15], v[132:135], v[250:253], v[12:15]
	v_mfma_f32_16x16x32_bf16 v[8:11], v[140:143], v[250:253], v[8:11]
	v_mfma_f32_16x16x32_bf16 v[60:63], v[176:179], v[192:195], v[60:63]
	v_mfma_f32_16x16x32_bf16 v[56:59], v[184:187], v[192:195], v[56:59]
	v_mfma_f32_16x16x32_bf16 v[36:39], v[176:179], v[210:213], v[36:39]
	v_mfma_f32_16x16x32_bf16 v[32:35], v[184:187], v[210:213], v[32:35]
	v_mfma_f32_16x16x32_bf16 v[20:23], v[176:179], v[238:241], v[20:23]
	v_mfma_f32_16x16x32_bf16 v[16:19], v[184:187], v[238:241], v[16:19]
	v_mfma_f32_16x16x32_bf16 v[4:7], v[176:179], v[246:249], v[4:7]
	v_mfma_f32_16x16x32_bf16 v[0:3], v[184:187], v[246:249], v[0:3]
	v_mfma_f32_16x16x32_bf16 v[60:63], v[180:183], v[196:199], v[60:63]
	v_mfma_f32_16x16x32_bf16 v[56:59], v[188:191], v[196:199], v[56:59]
	v_mfma_f32_16x16x32_bf16 v[36:39], v[180:183], v[214:217], v[36:39]
	v_mfma_f32_16x16x32_bf16 v[32:35], v[188:191], v[214:217], v[32:35]
	v_mfma_f32_16x16x32_bf16 v[20:23], v[180:183], v[242:245], v[20:23]
	v_mfma_f32_16x16x32_bf16 v[16:19], v[188:191], v[242:245], v[16:19]
	v_mfma_f32_16x16x32_bf16 v[4:7], v[180:183], v[250:253], v[4:7]
	v_mfma_f32_16x16x32_bf16 v[0:3], v[188:191], v[250:253], v[0:3]
	s_barrier
	s_cmp_gt_u32 s78, 13
	s_cbranch_scc0 .LBB0_119
	s_setprio 0
	s_and_b64 vcc, exec, s[18:19]
	s_cbranch_vccz .LBB0_122
	s_barrier

;     __host__ __device__ bool next(int i, Unit& u) const { return at((long)i * G + c, u); }
;     __host__ __device__ bool next(int i, Unit& u) const { if (i != 0 || c >= cnt) return false; u.pm = pm0 + c / nN; u.pn = c % nN; u.k0 = 0; u.nt = ntk; return true; }
; #define PG8_STAGE(bufoff, gbase, voff) do { _Pragma("unroll") for (int _i = 0; _i < 2; ++_i) \
;         __builtin_amdgcn_global_load_lds((const unsigned*)((const char*)(gbase) + (voff)[_i]), (PG8_LAS unsigned*)(lds + (bufoff) + ldsw + _i * 8192), 16, 0, 0); } while (0)
; #define PG8_BAR __builtin_amdgcn_s_barrier()
;     ...
;     for (;;) {
;         const bool has_next = S.next(ui + 1, nxt);
;         const char* nA = has_next ? (const char*)g.A + (size_t)nxt.pm * tstep + (size_t)nxt.k0 * (BK * 2) : cA; const char* nB = has_next ? (const char*)g.Bt + (size_t)nxt.pn * tstep + (size_t)nxt.k0 * (BK * 2) : cB;
;         const int nt = cur.nt;
;         for (int t = 0; t < nt; t += 2) {
;             const bool last = (t == nt - 2);
;             const char* a1 = cA + (size_t)(t + 1) * kstep;
;             const char* a2 = last ? nA : cA + (size_t)(t + 2) * kstep; const char* b2 = last ? nB : cB + (size_t)(t + 2) * kstep;
;             const char* a3 = a2 + kstep; const char* b3 = b2 + kstep;
;             if (last && has_next) S.a_ready(nxt);
;             if constexpr (SP2) {
;             PG8_LDB(B0, 0, 0); PG8_LDB(B1, 0, 1); PG8_SCHED; PG8_LDA(At, 0, 0); PG8_STAGEA(PG8_SA(1, 1), a1 + hstep, voffA);
;             PG8_WAIT_V(8); PG8_WAIT_L(0); PG8_BAR; PG8_MMA(0, 0, At, B0); PG8_MMA(0, 1, At, B1); PG8_BAR; PG8_SCHED;
;             PG8_LDA(At, 0, 1); PG8_STAGE(PG8_SB(0, 0), b2, voffB); PG8_STAGE(PG8_SB(0, 1), b2 + hstepB, voffB); PG8_STAGEA(PG8_SA(0, 0), a2, voffA);
;             PG8_WAIT_V(8); PG8_WAIT_L(0); PG8_BAR; PG8_MMA(1, 0, At, B0); PG8_MMA(1, 1, At, B1); PG8_BAR; PG8_SCHED;
;             PG8_LDB(B0, 1, 0); PG8_LDB(B1, 1, 1); PG8_SCHED; PG8_LDA(At, 1, 0); PG8_STAGEA(PG8_SA(0, 1), a2 + hstep, voffA);
;             PG8_WAIT_V(8); PG8_WAIT_L(0); PG8_BAR; PG8_MMA(0, 0, At, B0); PG8_MMA(0, 1, At, B1); PG8_BAR; PG8_SCHED;
;             PG8_LDA(At, 1, 1); PG8_STAGE(PG8_SB(1, 0), b3, voffB); PG8_STAGE(PG8_SB(1, 1), b3 + hstepB, voffB); PG8_STAGEA(PG8_SA(1, 0), a3, voffA);
;             PG8_WAIT_V(8); PG8_WAIT_L(0); PG8_BAR; PG8_MMA(1, 0, At, B0); PG8_MMA(1, 1, At, B1); PG8_BAR; PG8_SCHED;
.Lsprio_1:
.LBB0_444:
	ds_read_b128 v[148:151], v142
	ds_read_b128 v[152:155], v142 offset:1024
	ds_read_b128 v[156:159], v142 offset:2048
	ds_read_b128 v[160:163], v142 offset:3072
	ds_read_b128 v[164:167], v143
	ds_read_b128 v[168:171], v143 offset:1024
	ds_read_b128 v[176:179], v143 offset:2048
	ds_read_b128 v[180:183], v143 offset:3072
	s_add_u32 s14, s12, 0xf25c0080
	s_addc_u32 s15, s13, -1
	s_cmp_lg_u32 s22, 12
	s_cselect_b32 s14, s14, 0
	s_cselect_b32 s15, s15, 0
	s_add_u32 s16, s8, s14
	s_addc_u32 s17, s9, s15
	s_add_u32 s14, s6, s14
	s_addc_u32 s15, s7, s15
	s_mov_b32 m0, s23
	v_lshl_add_u64 v[172:173], v[136:137], 0, s[12:13]
	ds_read_b128 v[184:187], v144
	ds_read_b128 v[188:191], v144 offset:1024
	ds_read_b128 v[192:195], v144 offset:2048
	ds_read_b128 v[196:199], v144 offset:3072
	ds_read_b128 v[202:205], v144 offset:4096
	ds_read_b128 v[210:213], v144 offset:5120
	ds_read_b128 v[214:217], v144 offset:6144
	ds_read_b128 v[218:221], v144 offset:7168
	global_load_lds_dwordx4 v[172:173], off
	v_lshl_add_u64 v[172:173], v[138:139], 0, s[12:13]
	s_mov_b32 m0, s24
	s_nop 0
	global_load_lds_dwordx4 v[172:173], off
	s_waitcnt vmcnt(8)
	s_waitcnt lgkmcnt(0)
	s_barrier
	v_mfma_f32_16x16x32_bf16 v[124:127], v[148:151], v[184:187], v[124:127]
	v_mfma_f32_16x16x32_bf16 v[120:123], v[156:159], v[184:187], v[120:123]
	v_mfma_f32_16x16x32_bf16 v[108:111], v[148:151], v[192:195], v[108:111]
	v_mfma_f32_16x16x32_bf16 v[104:107], v[156:159], v[192:195], v[104:107]
	v_mfma_f32_16x16x32_bf16 v[92:95], v[148:151], v[202:205], v[92:95]
	v_mfma_f32_16x16x32_bf16 v[88:91], v[156:159], v[202:205], v[88:91]
	v_mfma_f32_16x16x32_bf16 v[76:79], v[148:151], v[214:217], v[76:79]
	v_mfma_f32_16x16x32_bf16 v[72:75], v[156:159], v[214:217], v[72:75]
	v_mfma_f32_16x16x32_bf16 v[124:127], v[152:155], v[188:191], v[124:127]
	v_mfma_f32_16x16x32_bf16 v[120:123], v[160:163], v[188:191], v[120:123]
	v_mfma_f32_16x16x32_bf16 v[108:111], v[152:155], v[196:199], v[108:111]
	v_mfma_f32_16x16x32_bf16 v[104:107], v[160:163], v[196:199], v[104:107]
	v_mfma_f32_16x16x32_bf16 v[92:95], v[152:155], v[210:213], v[92:95]
	v_mfma_f32_16x16x32_bf16 v[88:91], v[160:163], v[210:213], v[88:91]
	v_mfma_f32_16x16x32_bf16 v[76:79], v[152:155], v[218:221], v[76:79]
	v_mfma_f32_16x16x32_bf16 v[72:75], v[160:163], v[218:221], v[72:75]
	v_mfma_f32_16x16x32_bf16 v[116:119], v[164:167], v[184:187], v[116:119]
	v_mfma_f32_16x16x32_bf16 v[112:115], v[176:179], v[184:187], v[112:115]
	v_mfma_f32_16x16x32_bf16 v[100:103], v[164:167], v[192:195], v[100:103]
	v_mfma_f32_16x16x32_bf16 v[96:99], v[176:179], v[192:195], v[96:99]
	v_mfma_f32_16x16x32_bf16 v[84:87], v[164:167], v[202:205], v[84:87]
	v_mfma_f32_16x16x32_bf16 v[80:83], v[176:179], v[202:205], v[80:83]
	v_mfma_f32_16x16x32_bf16 v[68:71], v[164:167], v[214:217], v[68:71]
	v_mfma_f32_16x16x32_bf16 v[64:67], v[176:179], v[214:217], v[64:67]
	v_mfma_f32_16x16x32_bf16 v[116:119], v[168:171], v[188:191], v[116:119]
	v_mfma_f32_16x16x32_bf16 v[112:115], v[180:183], v[188:191], v[112:115]
	v_mfma_f32_16x16x32_bf16 v[100:103], v[168:171], v[196:199], v[100:103]
	v_mfma_f32_16x16x32_bf16 v[96:99], v[180:183], v[196:199], v[96:99]
	v_mfma_f32_16x16x32_bf16 v[84:87], v[168:171], v[210:213], v[84:87]
	v_mfma_f32_16x16x32_bf16 v[80:83], v[180:183], v[210:213], v[80:83]
	v_mfma_f32_16x16x32_bf16 v[68:71], v[168:171], v[218:221], v[68:71]
	v_mfma_f32_16x16x32_bf16 v[64:67], v[180:183], v[218:221], v[64:67]
	s_barrier
	s_mov_b32 m0, s25
	v_lshl_add_u64 v[172:173], s[14:15], 0, v[132:133]
	s_add_u32 s36, s14, 0x10000
	ds_read_b128 v[184:187], v144 offset:16384
	ds_read_b128 v[188:191], v144 offset:17408
	ds_read_b128 v[192:195], v144 offset:18432
	ds_read_b128 v[196:199], v144 offset:19456
	ds_read_b128 v[202:205], v144 offset:20480
	ds_read_b128 v[210:213], v144 offset:21504
	ds_read_b128 v[214:217], v144 offset:22528
	ds_read_b128 v[218:221], v144 offset:23552
	global_load_lds_dwordx4 v[172:173], off
	v_lshl_add_u64 v[206:207], s[14:15], 0, v[128:129]
	s_mov_b32 m0, s26
	s_addc_u32 s37, s15, 0
	global_load_lds_dwordx4 v[206:207], off
	v_lshl_add_u64 v[222:223], s[36:37], 0, v[132:133]
	s_mov_b32 m0, s27
	v_lshl_add_u64 v[224:225], s[16:17], 0, v[130:131]
	global_load_lds_dwordx4 v[222:223], off
	v_lshl_add_u64 v[222:223], s[36:37], 0, v[128:129]
	s_mov_b32 m0, s28
	s_nop 0
	global_load_lds_dwordx4 v[222:223], off
	v_lshl_add_u64 v[222:223], s[16:17], 0, v[134:135]
	s_mov_b32 m0, s1
	s_nop 0
	global_load_lds_dwordx4 v[222:223], off
	s_mov_b32 m0, s3
	s_nop 0
	global_load_lds_dwordx4 v[224:225], off
	s_waitcnt vmcnt(8)
	s_waitcnt lgkmcnt(0)
	s_barrier
; #define PG8_STAGE(bufoff, gbase, voff) do { _Pragma("unroll") for (int _i = 0; _i < 2; ++_i) \
;         __builtin_amdgcn_global_load_lds((const unsigned*)((const char*)(gbase) + (voff)[_i]), (PG8_LAS unsigned*)(lds + (bufoff) + ldsw + _i * 8192), 16, 0, 0); } while (0)
; #define PG8_STAGEA(bufoff, gbase, voff) do { _Pragma("unroll") for (int _i = 0; _i < 2; ++_i) \
;         __builtin_amdgcn_global_load_lds((const unsigned*)((const char*)(gbase) + (voff)[_i]), (PG8_LAS unsigned*)(lds + (bufoff) + ldsw + _i * 8192), 16, 0, AUXA); } while (0)
; #define PG8_LDA(dst, b, h) do { _Pragma("unroll") for (int m = 0; m < 4; ++m) _Pragma("unroll") for (int k = 0; k < 2; ++k) dst[m][k] = *(const PG8_LAS bf16x8*)(lds + PG8_SA(b, h) + aoff + m * 2048 + k * 1024); } while (0)
; #define PG8_LDB(dst, b, h) do { _Pragma("unroll") for (int n = 0; n < 2; ++n) _Pragma("unroll") for (int k = 0; k < 2; ++k) dst[n][k] = *(const PG8_LAS bf16x8*)(lds + PG8_SB(b, h) + boff + n * 2048 + k * 1024); } while (0)
; #define PG8_WAIT_V(n) asm volatile("s_waitcnt vmcnt(" #n ")" ::: "memory")
; #define PG8_WAIT_L(n) asm volatile("s_waitcnt lgkmcnt(" #n ")" ::: "memory")
; #define PG8_BAR __builtin_amdgcn_s_barrier()
; #define PG8_SCHED __builtin_amdgcn_sched_barrier(0)
;     ...
;             if constexpr (SP2) {
;             PG8_LDB(B0, 0, 0); PG8_LDB(B1, 0, 1); PG8_SCHED; PG8_LDA(At, 0, 0); PG8_STAGEA(PG8_SA(1, 1), a1 + hstep, voffA);
;             PG8_WAIT_V(8); PG8_WAIT_L(0); PG8_BAR; PG8_MMA(0, 0, At, B0); PG8_MMA(0, 1, At, B1); PG8_BAR; PG8_SCHED;
;             PG8_LDA(At, 0, 1); PG8_STAGE(PG8_SB(0, 0), b2, voffB); PG8_STAGE(PG8_SB(0, 1), b2 + hstepB, voffB); PG8_STAGEA(PG8_SA(0, 0), a2, voffA);
;             PG8_WAIT_V(8); PG8_WAIT_L(0); PG8_BAR; PG8_MMA(1, 0, At, B0); PG8_MMA(1, 1, At, B1); PG8_BAR; PG8_SCHED;
;             PG8_LDB(B0, 1, 0); PG8_LDB(B1, 1, 1); PG8_SCHED; PG8_LDA(At, 1, 0); PG8_STAGEA(PG8_SA(0, 1), a2 + hstep, voffA);
;             PG8_WAIT_V(8); PG8_WAIT_L(0); PG8_BAR; PG8_MMA(0, 0, At, B0); PG8_MMA(0, 1, At, B1); PG8_BAR; PG8_SCHED;
;             PG8_LDA(At, 1, 1); PG8_STAGE(PG8_SB(1, 0), b3, voffB); PG8_STAGE(PG8_SB(1, 1), b3 + hstepB, voffB); PG8_STAGEA(PG8_SA(1, 0), a3, voffA);
;             PG8_WAIT_V(8); PG8_WAIT_L(0); PG8_BAR; PG8_MMA(1, 0, At, B0); PG8_MMA(1, 1, At, B1); PG8_BAR; PG8_SCHED;
	v_mfma_f32_16x16x32_bf16 v[60:63], v[148:151], v[184:187], v[60:63]
	v_mfma_f32_16x16x32_bf16 v[56:59], v[156:159], v[184:187], v[56:59]
	v_mfma_f32_16x16x32_bf16 v[44:47], v[148:151], v[192:195], v[44:47]
	v_mfma_f32_16x16x32_bf16 v[40:43], v[156:159], v[192:195], v[40:43]
	v_mfma_f32_16x16x32_bf16 v[28:31], v[148:151], v[202:205], v[28:31]
	v_mfma_f32_16x16x32_bf16 v[24:27], v[156:159], v[202:205], v[24:27]
	v_mfma_f32_16x16x32_bf16 v[12:15], v[148:151], v[214:217], v[12:15]
	v_mfma_f32_16x16x32_bf16 v[8:11], v[156:159], v[214:217], v[8:11]
	v_mfma_f32_16x16x32_bf16 v[60:63], v[152:155], v[188:191], v[60:63]
	v_mfma_f32_16x16x32_bf16 v[56:59], v[160:163], v[188:191], v[56:59]
	v_mfma_f32_16x16x32_bf16 v[44:47], v[152:155], v[196:199], v[44:47]
	v_mfma_f32_16x16x32_bf16 v[40:43], v[160:163], v[196:199], v[40:43]
	v_mfma_f32_16x16x32_bf16 v[28:31], v[152:155], v[210:213], v[28:31]
	v_mfma_f32_16x16x32_bf16 v[24:27], v[160:163], v[210:213], v[24:27]
	v_mfma_f32_16x16x32_bf16 v[12:15], v[152:155], v[218:221], v[12:15]
	v_mfma_f32_16x16x32_bf16 v[8:11], v[160:163], v[218:221], v[8:11]
	v_mfma_f32_16x16x32_bf16 v[52:55], v[164:167], v[184:187], v[52:55]
	v_mfma_f32_16x16x32_bf16 v[48:51], v[176:179], v[184:187], v[48:51]
	v_mfma_f32_16x16x32_bf16 v[36:39], v[164:167], v[192:195], v[36:39]
	v_mfma_f32_16x16x32_bf16 v[32:35], v[176:179], v[192:195], v[32:35]
	v_mfma_f32_16x16x32_bf16 v[20:23], v[164:167], v[202:205], v[20:23]
	v_mfma_f32_16x16x32_bf16 v[16:19], v[176:179], v[202:205], v[16:19]
	v_mfma_f32_16x16x32_bf16 v[4:7], v[164:167], v[214:217], v[4:7]
	v_mfma_f32_16x16x32_bf16 v[0:3], v[176:179], v[214:217], v[0:3]
	v_mfma_f32_16x16x32_bf16 v[52:55], v[168:171], v[188:191], v[52:55]
	v_mfma_f32_16x16x32_bf16 v[48:51], v[180:183], v[188:191], v[48:51]
	v_mfma_f32_16x16x32_bf16 v[36:39], v[168:171], v[196:199], v[36:39]
	v_mfma_f32_16x16x32_bf16 v[32:35], v[180:183], v[196:199], v[32:35]
	v_mfma_f32_16x16x32_bf16 v[20:23], v[168:171], v[210:213], v[20:23]
	v_mfma_f32_16x16x32_bf16 v[16:19], v[180:183], v[210:213], v[16:19]
	v_mfma_f32_16x16x32_bf16 v[4:7], v[168:171], v[218:221], v[4:7]
	v_mfma_f32_16x16x32_bf16 v[0:3], v[180:183], v[218:221], v[0:3]
	s_barrier
	ds_read_b128 v[148:151], v145
	ds_read_b128 v[152:155], v145 offset:1024
	ds_read_b128 v[156:159], v145 offset:2048
	ds_read_b128 v[160:163], v145 offset:3072
	ds_read_b128 v[164:167], v146
	ds_read_b128 v[168:171], v146 offset:1024
	ds_read_b128 v[176:179], v146 offset:2048
	ds_read_b128 v[180:183], v146 offset:3072
	s_add_u32 s16, s16, 0x40000
	s_addc_u32 s17, s17, 0
	s_mov_b32 m0, s18
	v_lshl_add_u64 v[226:227], s[16:17], 0, v[134:135]
	ds_read_b128 v[184:187], v144 offset:32768
	ds_read_b128 v[188:191], v144 offset:33792
	ds_read_b128 v[192:195], v144 offset:34816
	ds_read_b128 v[196:199], v144 offset:35840
	ds_read_b128 v[202:205], v144 offset:36864
	ds_read_b128 v[210:213], v144 offset:37888
	ds_read_b128 v[214:217], v144 offset:38912
	ds_read_b128 v[218:221], v144 offset:39936
	global_load_lds_dwordx4 v[226:227], off
	v_lshl_add_u64 v[226:227], s[16:17], 0, v[130:131]
	s_mov_b32 m0, s19
	s_nop 0
	global_load_lds_dwordx4 v[226:227], off
	s_waitcnt vmcnt(8)
	s_waitcnt lgkmcnt(0)
	s_barrier
	v_mfma_f32_16x16x32_bf16 v[124:127], v[148:151], v[184:187], v[124:127]
	v_mfma_f32_16x16x32_bf16 v[120:123], v[156:159], v[184:187], v[120:123]
	v_mfma_f32_16x16x32_bf16 v[108:111], v[148:151], v[192:195], v[108:111]
	v_mfma_f32_16x16x32_bf16 v[104:107], v[156:159], v[192:195], v[104:107]
	v_mfma_f32_16x16x32_bf16 v[92:95], v[148:151], v[202:205], v[92:95]
	v_mfma_f32_16x16x32_bf16 v[88:91], v[156:159], v[202:205], v[88:91]
	v_mfma_f32_16x16x32_bf16 v[76:79], v[148:151], v[214:217], v[76:79]
	v_mfma_f32_16x16x32_bf16 v[72:75], v[156:159], v[214:217], v[72:75]
	v_mfma_f32_16x16x32_bf16 v[124:127], v[152:155], v[188:191], v[124:127]
	v_mfma_f32_16x16x32_bf16 v[120:123], v[160:163], v[188:191], v[120:123]
	v_mfma_f32_16x16x32_bf16 v[108:111], v[152:155], v[196:199], v[108:111]
	v_mfma_f32_16x16x32_bf16 v[104:107], v[160:163], v[196:199], v[104:107]
	v_mfma_f32_16x16x32_bf16 v[92:95], v[152:155], v[210:213], v[92:95]
	v_mfma_f32_16x16x32_bf16 v[88:91], v[160:163], v[210:213], v[88:91]
	v_mfma_f32_16x16x32_bf16 v[76:79], v[152:155], v[218:221], v[76:79]
	v_mfma_f32_16x16x32_bf16 v[72:75], v[160:163], v[218:221], v[72:75]
	v_mfma_f32_16x16x32_bf16 v[116:119], v[164:167], v[184:187], v[116:119]
	v_mfma_f32_16x16x32_bf16 v[112:115], v[176:179], v[184:187], v[112:115]
	v_mfma_f32_16x16x32_bf16 v[100:103], v[164:167], v[192:195], v[100:103]
	v_mfma_f32_16x16x32_bf16 v[96:99], v[176:179], v[192:195], v[96:99]
	v_mfma_f32_16x16x32_bf16 v[84:87], v[164:167], v[202:205], v[84:87]
	v_mfma_f32_16x16x32_bf16 v[80:83], v[176:179], v[202:205], v[80:83]
	v_mfma_f32_16x16x32_bf16 v[68:71], v[164:167], v[214:217], v[68:71]
	v_mfma_f32_16x16x32_bf16 v[64:67], v[176:179], v[214:217], v[64:67]
	v_mfma_f32_16x16x32_bf16 v[116:119], v[168:171], v[188:191], v[116:119]
	v_mfma_f32_16x16x32_bf16 v[112:115], v[180:183], v[188:191], v[112:115]
	v_mfma_f32_16x16x32_bf16 v[100:103], v[168:171], v[196:199], v[100:103]
	v_mfma_f32_16x16x32_bf16 v[96:99], v[180:183], v[196:199], v[96:99]
	v_mfma_f32_16x16x32_bf16 v[84:87], v[168:171], v[210:213], v[84:87]
	v_mfma_f32_16x16x32_bf16 v[80:83], v[180:183], v[210:213], v[80:83]
	v_mfma_f32_16x16x32_bf16 v[68:71], v[168:171], v[218:221], v[68:71]
	v_mfma_f32_16x16x32_bf16 v[64:67], v[180:183], v[218:221], v[64:67]
	s_barrier
; #define PG8_STAGE(bufoff, gbase, voff) do { _Pragma("unroll") for (int _i = 0; _i < 2; ++_i) \
;         __builtin_amdgcn_global_load_lds((const unsigned*)((const char*)(gbase) + (voff)[_i]), (PG8_LAS unsigned*)(lds + (bufoff) + ldsw + _i * 8192), 16, 0, 0); } while (0)
; #define PG8_STAGEA(bufoff, gbase, voff) do { _Pragma("unroll") for (int _i = 0; _i < 2; ++_i) \
;         __builtin_amdgcn_global_load_lds((const unsigned*)((const char*)(gbase) + (voff)[_i]), (PG8_LAS unsigned*)(lds + (bufoff) + ldsw + _i * 8192), 16, 0, AUXA); } while (0)
; #define PG8_LDA(dst, b, h) do { _Pragma("unroll") for (int m = 0; m < 4; ++m) _Pragma("unroll") for (int k = 0; k < 2; ++k) dst[m][k] = *(const PG8_LAS bf16x8*)(lds + PG8_SA(b, h) + aoff + m * 2048 + k * 1024); } while (0)
; #define PG8_LDB(dst, b, h) do { _Pragma("unroll") for (int n = 0; n < 2; ++n) _Pragma("unroll") for (int k = 0; k < 2; ++k) dst[n][k] = *(const PG8_LAS bf16x8*)(lds + PG8_SB(b, h) + boff + n * 2048 + k * 1024); } while (0)
; #define PG8_WAIT_V(n) asm volatile("s_waitcnt vmcnt(" #n ")" ::: "memory")
; #define PG8_WAIT_L(n) asm volatile("s_waitcnt lgkmcnt(" #n ")" ::: "memory")
; #define PG8_BAR __builtin_amdgcn_s_barrier()
; #define PG8_SCHED __builtin_amdgcn_sched_barrier(0)
;     ...
;             if constexpr (SP2) {
;             PG8_LDB(B0, 0, 0); PG8_LDB(B1, 0, 1); PG8_SCHED; PG8_LDA(At, 0, 0); PG8_STAGEA(PG8_SA(1, 1), a1 + hstep, voffA);
;             PG8_WAIT_V(8); PG8_WAIT_L(0); PG8_BAR; PG8_MMA(0, 0, At, B0); PG8_MMA(0, 1, At, B1); PG8_BAR; PG8_SCHED;
;             PG8_LDA(At, 0, 1); PG8_STAGE(PG8_SB(0, 0), b2, voffB); PG8_STAGE(PG8_SB(0, 1), b2 + hstepB, voffB); PG8_STAGEA(PG8_SA(0, 0), a2, voffA);
;             PG8_WAIT_V(8); PG8_WAIT_L(0); PG8_BAR; PG8_MMA(1, 0, At, B0); PG8_MMA(1, 1, At, B1); PG8_BAR; PG8_SCHED;
;             PG8_LDB(B0, 1, 0); PG8_LDB(B1, 1, 1); PG8_SCHED; PG8_LDA(At, 1, 0); PG8_STAGEA(PG8_SA(0, 1), a2 + hstep, voffA);
;             PG8_WAIT_V(8); PG8_WAIT_L(0); PG8_BAR; PG8_MMA(0, 0, At, B0); PG8_MMA(0, 1, At, B1); PG8_BAR; PG8_SCHED;
;             PG8_LDA(At, 1, 1); PG8_STAGE(PG8_SB(1, 0), b3, voffB); PG8_STAGE(PG8_SB(1, 1), b3 + hstepB, voffB); PG8_STAGEA(PG8_SA(1, 0), a3, voffA);
;             PG8_WAIT_V(8); PG8_WAIT_L(0); PG8_BAR; PG8_MMA(1, 0, At, B0); PG8_MMA(1, 1, At, B1); PG8_BAR; PG8_SCHED;
;     ...
;         if constexpr (ALIGN_EPI) { if (wr == 0) PG8_BAR; }
	s_mov_b32 m0, s29
	v_lshl_add_u64 v[172:173], v[172:173], 0, s[10:11]
	s_add_u32 s14, s14, 0x10080
	ds_read_b128 v[184:187], v144 offset:49152
	ds_read_b128 v[188:191], v144 offset:50176
	ds_read_b128 v[192:195], v144 offset:51200
	ds_read_b128 v[196:199], v144 offset:52224
	ds_read_b128 v[202:205], v144 offset:53248
	ds_read_b128 v[210:213], v144 offset:54272
	ds_read_b128 v[214:217], v144 offset:55296
	ds_read_b128 v[218:221], v144 offset:56320
	global_load_lds_dwordx4 v[172:173], off
	v_lshl_add_u64 v[172:173], v[206:207], 0, s[10:11]
	s_mov_b32 m0, s30
	s_addc_u32 s15, s15, 0
	global_load_lds_dwordx4 v[172:173], off
	v_lshl_add_u64 v[172:173], s[14:15], 0, v[132:133]
	s_mov_b32 m0, s31
	s_nop 0
	global_load_lds_dwordx4 v[172:173], off
	v_lshl_add_u64 v[172:173], s[14:15], 0, v[128:129]
	s_mov_b32 m0, s34
	s_nop 0
	global_load_lds_dwordx4 v[172:173], off
	v_lshl_add_u64 v[172:173], v[222:223], 0, s[10:11]
	s_mov_b32 m0, s20
	s_nop 0
	global_load_lds_dwordx4 v[172:173], off
	v_lshl_add_u64 v[172:173], v[224:225], 0, s[10:11]
	s_mov_b32 m0, s21
	s_nop 0
	global_load_lds_dwordx4 v[172:173], off
	s_waitcnt vmcnt(8)
	s_waitcnt lgkmcnt(0)
	s_barrier
	v_mfma_f32_16x16x32_bf16 v[60:63], v[148:151], v[184:187], v[60:63]
	v_mfma_f32_16x16x32_bf16 v[56:59], v[156:159], v[184:187], v[56:59]
	v_mfma_f32_16x16x32_bf16 v[44:47], v[148:151], v[192:195], v[44:47]
	s_add_i32 s22, s22, 2
	v_mfma_f32_16x16x32_bf16 v[40:43], v[156:159], v[192:195], v[40:43]
	v_mfma_f32_16x16x32_bf16 v[28:31], v[148:151], v[202:205], v[28:31]
	s_add_u32 s12, s12, 0x100
	v_mfma_f32_16x16x32_bf16 v[24:27], v[156:159], v[202:205], v[24:27]
	v_mfma_f32_16x16x32_bf16 v[12:15], v[148:151], v[214:217], v[12:15]
	s_addc_u32 s13, s13, 0
	v_mfma_f32_16x16x32_bf16 v[8:11], v[156:159], v[214:217], v[8:11]
	v_mfma_f32_16x16x32_bf16 v[60:63], v[152:155], v[188:191], v[60:63]
	v_mfma_f32_16x16x32_bf16 v[56:59], v[160:163], v[188:191], v[56:59]
	v_mfma_f32_16x16x32_bf16 v[44:47], v[152:155], v[196:199], v[44:47]
	v_mfma_f32_16x16x32_bf16 v[40:43], v[160:163], v[196:199], v[40:43]
	v_mfma_f32_16x16x32_bf16 v[28:31], v[152:155], v[210:213], v[28:31]
	v_mfma_f32_16x16x32_bf16 v[24:27], v[160:163], v[210:213], v[24:27]
	v_mfma_f32_16x16x32_bf16 v[12:15], v[152:155], v[218:221], v[12:15]
	v_mfma_f32_16x16x32_bf16 v[8:11], v[160:163], v[218:221], v[8:11]
	v_mfma_f32_16x16x32_bf16 v[52:55], v[164:167], v[184:187], v[52:55]
	v_mfma_f32_16x16x32_bf16 v[48:51], v[176:179], v[184:187], v[48:51]
	v_mfma_f32_16x16x32_bf16 v[36:39], v[164:167], v[192:195], v[36:39]
	v_mfma_f32_16x16x32_bf16 v[32:35], v[176:179], v[192:195], v[32:35]
	v_mfma_f32_16x16x32_bf16 v[20:23], v[164:167], v[202:205], v[20:23]
	v_mfma_f32_16x16x32_bf16 v[16:19], v[176:179], v[202:205], v[16:19]
	v_mfma_f32_16x16x32_bf16 v[4:7], v[164:167], v[214:217], v[4:7]
	v_mfma_f32_16x16x32_bf16 v[0:3], v[176:179], v[214:217], v[0:3]
	v_mfma_f32_16x16x32_bf16 v[52:55], v[168:171], v[188:191], v[52:55]
	v_mfma_f32_16x16x32_bf16 v[48:51], v[180:183], v[188:191], v[48:51]
	v_mfma_f32_16x16x32_bf16 v[36:39], v[168:171], v[196:199], v[36:39]
	v_mfma_f32_16x16x32_bf16 v[32:35], v[180:183], v[196:199], v[32:35]
	v_mfma_f32_16x16x32_bf16 v[20:23], v[168:171], v[210:213], v[20:23]
	v_mfma_f32_16x16x32_bf16 v[16:19], v[180:183], v[210:213], v[16:19]
	v_mfma_f32_16x16x32_bf16 v[4:7], v[168:171], v[218:221], v[4:7]
	v_mfma_f32_16x16x32_bf16 v[0:3], v[180:183], v[218:221], v[0:3]
	s_barrier
	s_cmp_gt_u32 s22, 13
	s_cbranch_scc0 .LBB0_444
	s_setprio 0
	v_readlane_b32 s1, v255, 10
	s_cmpk_lt_u32 s1, 0x100
	s_cbranch_scc0 .LBB0_447
	s_barrier

;     __host__ __device__ bool next(int i, Unit& u) const { return at((long)i * G + c, u); }
;     __host__ __device__ bool next(int i, Unit& u) const { if (i != 0 || c >= cnt) return false; u.pm = pm0 + c / nN; u.pn = c % nN; u.k0 = 0; u.nt = ntk; return true; }
; #define PG8_STAGE(bufoff, gbase, voff) do { _Pragma("unroll") for (int _i = 0; _i < 2; ++_i) \
;         __builtin_amdgcn_global_load_lds((const unsigned*)((const char*)(gbase) + (voff)[_i]), (PG8_LAS unsigned*)(lds + (bufoff) + ldsw + _i * 8192), 16, 0, 0); } while (0)
; #define PG8_BAR __builtin_amdgcn_s_barrier()
;     ...
;     for (;;) {
;         const bool has_next = S.next(ui + 1, nxt);
;         const char* nA = has_next ? (const char*)g.A + (size_t)nxt.pm * tstep + (size_t)nxt.k0 * (BK * 2) : cA; const char* nB = has_next ? (const char*)g.Bt + (size_t)nxt.pn * tstep + (size_t)nxt.k0 * (BK * 2) : cB;
;         const int nt = cur.nt;
;         for (int t = 0; t < nt; t += 2) {
;             const bool last = (t == nt - 2);
;             const char* a1 = cA + (size_t)(t + 1) * kstep;
;             const char* a2 = last ? nA : cA + (size_t)(t + 2) * kstep; const char* b2 = last ? nB : cB + (size_t)(t + 2) * kstep;
;             const char* a3 = a2 + kstep; const char* b3 = b2 + kstep;
;             if (last && has_next) S.a_ready(nxt);
;             if constexpr (SP2) {
;             PG8_LDB(B0, 0, 0); PG8_LDB(B1, 0, 1); PG8_SCHED; PG8_LDA(At, 0, 0); PG8_STAGEA(PG8_SA(1, 1), a1 + hstep, voffA);
;             PG8_WAIT_V(8); PG8_WAIT_L(0); PG8_BAR; PG8_MMA(0, 0, At, B0); PG8_MMA(0, 1, At, B1); PG8_BAR; PG8_SCHED;
;             PG8_LDA(At, 0, 1); PG8_STAGE(PG8_SB(0, 0), b2, voffB); PG8_STAGE(PG8_SB(0, 1), b2 + hstepB, voffB); PG8_STAGEA(PG8_SA(0, 0), a2, voffA);
;             PG8_WAIT_V(8); PG8_WAIT_L(0); PG8_BAR; PG8_MMA(1, 0, At, B0); PG8_MMA(1, 1, At, B1); PG8_BAR; PG8_SCHED;
;             PG8_LDB(B0, 1, 0); PG8_LDB(B1, 1, 1); PG8_SCHED; PG8_LDA(At, 1, 0); PG8_STAGEA(PG8_SA(0, 1), a2 + hstep, voffA);
;             PG8_WAIT_V(8); PG8_WAIT_L(0); PG8_BAR; PG8_MMA(0, 0, At, B0); PG8_MMA(0, 1, At, B1); PG8_BAR; PG8_SCHED;
;             PG8_LDA(At, 1, 1); PG8_STAGE(PG8_SB(1, 0), b3, voffB); PG8_STAGE(PG8_SB(1, 1), b3 + hstepB, voffB); PG8_STAGEA(PG8_SA(1, 0), a3, voffA);
;             PG8_WAIT_V(8); PG8_WAIT_L(0); PG8_BAR; PG8_MMA(1, 0, At, B0); PG8_MMA(1, 1, At, B1); PG8_BAR; PG8_SCHED;
.Lsprio_2:
.LBB0_758:
	ds_read_b128 v[148:151], v142
	ds_read_b128 v[152:155], v142 offset:1024
	ds_read_b128 v[156:159], v142 offset:2048
	ds_read_b128 v[160:163], v142 offset:3072
	ds_read_b128 v[164:167], v143
	ds_read_b128 v[168:171], v143 offset:1024
	ds_read_b128 v[176:179], v143 offset:2048
	ds_read_b128 v[180:183], v143 offset:3072
	s_add_u32 s14, s12, 0xf03c0080
	s_addc_u32 s15, s13, -1
	s_cmp_lg_u32 s22, 12
	s_cselect_b32 s14, s14, 0
	s_cselect_b32 s15, s15, 0
	s_add_u32 s16, s8, s14
	s_addc_u32 s17, s9, s15
	s_add_u32 s14, s6, s14
	s_addc_u32 s15, s7, s15
	s_mov_b32 m0, s23
	v_lshl_add_u64 v[172:173], v[138:139], 0, s[12:13]
	ds_read_b128 v[184:187], v144
	ds_read_b128 v[188:191], v144 offset:1024
	ds_read_b128 v[192:195], v144 offset:2048
	ds_read_b128 v[196:199], v144 offset:3072
	ds_read_b128 v[202:205], v144 offset:4096
	ds_read_b128 v[210:213], v144 offset:5120
	ds_read_b128 v[214:217], v144 offset:6144
	ds_read_b128 v[218:221], v144 offset:7168
	global_load_lds_dwordx4 v[172:173], off
	v_lshl_add_u64 v[172:173], v[140:141], 0, s[12:13]
	s_mov_b32 m0, s24
	s_nop 0
	global_load_lds_dwordx4 v[172:173], off
	s_waitcnt vmcnt(8)
	s_waitcnt lgkmcnt(0)
	s_barrier
	v_mfma_f32_16x16x32_bf16 v[124:127], v[148:151], v[184:187], v[124:127]
	v_mfma_f32_16x16x32_bf16 v[120:123], v[156:159], v[184:187], v[120:123]
	v_mfma_f32_16x16x32_bf16 v[108:111], v[148:151], v[192:195], v[108:111]
	v_mfma_f32_16x16x32_bf16 v[104:107], v[156:159], v[192:195], v[104:107]
	v_mfma_f32_16x16x32_bf16 v[92:95], v[148:151], v[202:205], v[92:95]
	v_mfma_f32_16x16x32_bf16 v[88:91], v[156:159], v[202:205], v[88:91]
	v_mfma_f32_16x16x32_bf16 v[76:79], v[148:151], v[214:217], v[76:79]
	v_mfma_f32_16x16x32_bf16 v[72:75], v[156:159], v[214:217], v[72:75]
	v_mfma_f32_16x16x32_bf16 v[124:127], v[152:155], v[188:191], v[124:127]
	v_mfma_f32_16x16x32_bf16 v[120:123], v[160:163], v[188:191], v[120:123]
	v_mfma_f32_16x16x32_bf16 v[108:111], v[152:155], v[196:199], v[108:111]
	v_mfma_f32_16x16x32_bf16 v[104:107], v[160:163], v[196:199], v[104:107]
	v_mfma_f32_16x16x32_bf16 v[92:95], v[152:155], v[210:213], v[92:95]
	v_mfma_f32_16x16x32_bf16 v[88:91], v[160:163], v[210:213], v[88:91]
	v_mfma_f32_16x16x32_bf16 v[76:79], v[152:155], v[218:221], v[76:79]
	v_mfma_f32_16x16x32_bf16 v[72:75], v[160:163], v[218:221], v[72:75]
	v_mfma_f32_16x16x32_bf16 v[116:119], v[164:167], v[184:187], v[116:119]
	v_mfma_f32_16x16x32_bf16 v[112:115], v[176:179], v[184:187], v[112:115]
	v_mfma_f32_16x16x32_bf16 v[100:103], v[164:167], v[192:195], v[100:103]
	v_mfma_f32_16x16x32_bf16 v[96:99], v[176:179], v[192:195], v[96:99]
	v_mfma_f32_16x16x32_bf16 v[84:87], v[164:167], v[202:205], v[84:87]
	v_mfma_f32_16x16x32_bf16 v[80:83], v[176:179], v[202:205], v[80:83]
	v_mfma_f32_16x16x32_bf16 v[68:71], v[164:167], v[214:217], v[68:71]
	v_mfma_f32_16x16x32_bf16 v[64:67], v[176:179], v[214:217], v[64:67]
	v_mfma_f32_16x16x32_bf16 v[116:119], v[168:171], v[188:191], v[116:119]
	v_mfma_f32_16x16x32_bf16 v[112:115], v[180:183], v[188:191], v[112:115]
	v_mfma_f32_16x16x32_bf16 v[100:103], v[168:171], v[196:199], v[100:103]
	v_mfma_f32_16x16x32_bf16 v[96:99], v[180:183], v[196:199], v[96:99]
	v_mfma_f32_16x16x32_bf16 v[84:87], v[168:171], v[210:213], v[84:87]
	v_mfma_f32_16x16x32_bf16 v[80:83], v[180:183], v[210:213], v[80:83]
	v_mfma_f32_16x16x32_bf16 v[68:71], v[168:171], v[218:221], v[68:71]
	v_mfma_f32_16x16x32_bf16 v[64:67], v[180:183], v[218:221], v[64:67]
	s_barrier
	s_mov_b32 m0, s25
	v_lshl_add_u64 v[172:173], s[14:15], 0, v[134:135]
	s_add_u32 s36, s14, 0x10000
	ds_read_b128 v[184:187], v144 offset:16384
	ds_read_b128 v[188:191], v144 offset:17408
	ds_read_b128 v[192:195], v144 offset:18432
	ds_read_b128 v[196:199], v144 offset:19456
	ds_read_b128 v[202:205], v144 offset:20480
	ds_read_b128 v[210:213], v144 offset:21504
	ds_read_b128 v[214:217], v144 offset:22528
	ds_read_b128 v[218:221], v144 offset:23552
	global_load_lds_dwordx4 v[172:173], off
	v_lshl_add_u64 v[206:207], s[14:15], 0, v[130:131]
	s_mov_b32 m0, s26
	s_addc_u32 s37, s15, 0
	global_load_lds_dwordx4 v[206:207], off
	v_lshl_add_u64 v[222:223], s[36:37], 0, v[134:135]
	s_mov_b32 m0, s27
	v_lshl_add_u64 v[224:225], s[16:17], 0, v[132:133]
	global_load_lds_dwordx4 v[222:223], off
	v_lshl_add_u64 v[222:223], s[36:37], 0, v[130:131]
	s_mov_b32 m0, s28
	s_nop 0
	global_load_lds_dwordx4 v[222:223], off
	v_lshl_add_u64 v[222:223], s[16:17], 0, v[136:137]
	s_mov_b32 m0, s1
	s_nop 0
	global_load_lds_dwordx4 v[222:223], off
	s_mov_b32 m0, s5
	s_nop 0
	global_load_lds_dwordx4 v[224:225], off
	s_waitcnt vmcnt(8)
	s_waitcnt lgkmcnt(0)
	s_barrier
; #define PG8_STAGE(bufoff, gbase, voff) do { _Pragma("unroll") for (int _i = 0; _i < 2; ++_i) \
;         __builtin_amdgcn_global_load_lds((const unsigned*)((const char*)(gbase) + (voff)[_i]), (PG8_LAS unsigned*)(lds + (bufoff) + ldsw + _i * 8192), 16, 0, 0); } while (0)
; #define PG8_STAGEA(bufoff, gbase, voff) do { _Pragma("unroll") for (int _i = 0; _i < 2; ++_i) \
;         __builtin_amdgcn_global_load_lds((const unsigned*)((const char*)(gbase) + (voff)[_i]), (PG8_LAS unsigned*)(lds + (bufoff) + ldsw + _i * 8192), 16, 0, AUXA); } while (0)
; #define PG8_LDA(dst, b, h) do { _Pragma("unroll") for (int m = 0; m < 4; ++m) _Pragma("unroll") for (int k = 0; k < 2; ++k) dst[m][k] = *(const PG8_LAS bf16x8*)(lds + PG8_SA(b, h) + aoff + m * 2048 + k * 1024); } while (0)
; #define PG8_LDB(dst, b, h) do { _Pragma("unroll") for (int n = 0; n < 2; ++n) _Pragma("unroll") for (int k = 0; k < 2; ++k) dst[n][k] = *(const PG8_LAS bf16x8*)(lds + PG8_SB(b, h) + boff + n * 2048 + k * 1024); } while (0)
; #define PG8_WAIT_V(n) asm volatile("s_waitcnt vmcnt(" #n ")" ::: "memory")
; #define PG8_WAIT_L(n) asm volatile("s_waitcnt lgkmcnt(" #n ")" ::: "memory")
; #define PG8_BAR __builtin_amdgcn_s_barrier()
; #define PG8_SCHED __builtin_amdgcn_sched_barrier(0)
;     ...
;             if constexpr (SP2) {
;             PG8_LDB(B0, 0, 0); PG8_LDB(B1, 0, 1); PG8_SCHED; PG8_LDA(At, 0, 0); PG8_STAGEA(PG8_SA(1, 1), a1 + hstep, voffA);
;             PG8_WAIT_V(8); PG8_WAIT_L(0); PG8_BAR; PG8_MMA(0, 0, At, B0); PG8_MMA(0, 1, At, B1); PG8_BAR; PG8_SCHED;
;             PG8_LDA(At, 0, 1); PG8_STAGE(PG8_SB(0, 0), b2, voffB); PG8_STAGE(PG8_SB(0, 1), b2 + hstepB, voffB); PG8_STAGEA(PG8_SA(0, 0), a2, voffA);
;             PG8_WAIT_V(8); PG8_WAIT_L(0); PG8_BAR; PG8_MMA(1, 0, At, B0); PG8_MMA(1, 1, At, B1); PG8_BAR; PG8_SCHED;
;             PG8_LDB(B0, 1, 0); PG8_LDB(B1, 1, 1); PG8_SCHED; PG8_LDA(At, 1, 0); PG8_STAGEA(PG8_SA(0, 1), a2 + hstep, voffA);
;             PG8_WAIT_V(8); PG8_WAIT_L(0); PG8_BAR; PG8_MMA(0, 0, At, B0); PG8_MMA(0, 1, At, B1); PG8_BAR; PG8_SCHED;
;             PG8_LDA(At, 1, 1); PG8_STAGE(PG8_SB(1, 0), b3, voffB); PG8_STAGE(PG8_SB(1, 1), b3 + hstepB, voffB); PG8_STAGEA(PG8_SA(1, 0), a3, voffA);
;             PG8_WAIT_V(8); PG8_WAIT_L(0); PG8_BAR; PG8_MMA(1, 0, At, B0); PG8_MMA(1, 1, At, B1); PG8_BAR; PG8_SCHED;
	v_mfma_f32_16x16x32_bf16 v[60:63], v[148:151], v[184:187], v[60:63]
	v_mfma_f32_16x16x32_bf16 v[56:59], v[156:159], v[184:187], v[56:59]
	v_mfma_f32_16x16x32_bf16 v[44:47], v[148:151], v[192:195], v[44:47]
	v_mfma_f32_16x16x32_bf16 v[40:43], v[156:159], v[192:195], v[40:43]
	v_mfma_f32_16x16x32_bf16 v[28:31], v[148:151], v[202:205], v[28:31]
	v_mfma_f32_16x16x32_bf16 v[24:27], v[156:159], v[202:205], v[24:27]
	v_mfma_f32_16x16x32_bf16 v[12:15], v[148:151], v[214:217], v[12:15]
	v_mfma_f32_16x16x32_bf16 v[8:11], v[156:159], v[214:217], v[8:11]
	v_mfma_f32_16x16x32_bf16 v[60:63], v[152:155], v[188:191], v[60:63]
	v_mfma_f32_16x16x32_bf16 v[56:59], v[160:163], v[188:191], v[56:59]
	v_mfma_f32_16x16x32_bf16 v[44:47], v[152:155], v[196:199], v[44:47]
	v_mfma_f32_16x16x32_bf16 v[40:43], v[160:163], v[196:199], v[40:43]
	v_mfma_f32_16x16x32_bf16 v[28:31], v[152:155], v[210:213], v[28:31]
	v_mfma_f32_16x16x32_bf16 v[24:27], v[160:163], v[210:213], v[24:27]
	v_mfma_f32_16x16x32_bf16 v[12:15], v[152:155], v[218:221], v[12:15]
	v_mfma_f32_16x16x32_bf16 v[8:11], v[160:163], v[218:221], v[8:11]
	v_mfma_f32_16x16x32_bf16 v[52:55], v[164:167], v[184:187], v[52:55]
	v_mfma_f32_16x16x32_bf16 v[48:51], v[176:179], v[184:187], v[48:51]
	v_mfma_f32_16x16x32_bf16 v[36:39], v[164:167], v[192:195], v[36:39]
	v_mfma_f32_16x16x32_bf16 v[32:35], v[176:179], v[192:195], v[32:35]
	v_mfma_f32_16x16x32_bf16 v[20:23], v[164:167], v[202:205], v[20:23]
	v_mfma_f32_16x16x32_bf16 v[16:19], v[176:179], v[202:205], v[16:19]
	v_mfma_f32_16x16x32_bf16 v[4:7], v[164:167], v[214:217], v[4:7]
	v_mfma_f32_16x16x32_bf16 v[0:3], v[176:179], v[214:217], v[0:3]
	v_mfma_f32_16x16x32_bf16 v[52:55], v[168:171], v[188:191], v[52:55]
	v_mfma_f32_16x16x32_bf16 v[48:51], v[180:183], v[188:191], v[48:51]
	v_mfma_f32_16x16x32_bf16 v[36:39], v[168:171], v[196:199], v[36:39]
	v_mfma_f32_16x16x32_bf16 v[32:35], v[180:183], v[196:199], v[32:35]
	v_mfma_f32_16x16x32_bf16 v[20:23], v[168:171], v[210:213], v[20:23]
	v_mfma_f32_16x16x32_bf16 v[16:19], v[180:183], v[210:213], v[16:19]
	v_mfma_f32_16x16x32_bf16 v[4:7], v[168:171], v[218:221], v[4:7]
	v_mfma_f32_16x16x32_bf16 v[0:3], v[180:183], v[218:221], v[0:3]
	s_barrier
	ds_read_b128 v[148:151], v145
	ds_read_b128 v[152:155], v145 offset:1024
	ds_read_b128 v[156:159], v145 offset:2048
	ds_read_b128 v[160:163], v145 offset:3072
	ds_read_b128 v[164:167], v146
	ds_read_b128 v[168:171], v146 offset:1024
	ds_read_b128 v[176:179], v146 offset:2048
	ds_read_b128 v[180:183], v146 offset:3072
	s_add_u32 s16, s16, 0x40000
	s_addc_u32 s17, s17, 0
	s_mov_b32 m0, s18
	v_lshl_add_u64 v[226:227], s[16:17], 0, v[136:137]
	ds_read_b128 v[184:187], v144 offset:32768
	ds_read_b128 v[188:191], v144 offset:33792
	ds_read_b128 v[192:195], v144 offset:34816
	ds_read_b128 v[196:199], v144 offset:35840
	ds_read_b128 v[202:205], v144 offset:36864
	ds_read_b128 v[210:213], v144 offset:37888
	ds_read_b128 v[214:217], v144 offset:38912
	ds_read_b128 v[218:221], v144 offset:39936
	global_load_lds_dwordx4 v[226:227], off
	v_lshl_add_u64 v[226:227], s[16:17], 0, v[132:133]
	s_mov_b32 m0, s19
	s_nop 0
	global_load_lds_dwordx4 v[226:227], off
	s_waitcnt vmcnt(8)
	s_waitcnt lgkmcnt(0)
	s_barrier
	v_mfma_f32_16x16x32_bf16 v[124:127], v[148:151], v[184:187], v[124:127]
	v_mfma_f32_16x16x32_bf16 v[120:123], v[156:159], v[184:187], v[120:123]
	v_mfma_f32_16x16x32_bf16 v[108:111], v[148:151], v[192:195], v[108:111]
	v_mfma_f32_16x16x32_bf16 v[104:107], v[156:159], v[192:195], v[104:107]
	v_mfma_f32_16x16x32_bf16 v[92:95], v[148:151], v[202:205], v[92:95]
	v_mfma_f32_16x16x32_bf16 v[88:91], v[156:159], v[202:205], v[88:91]
	v_mfma_f32_16x16x32_bf16 v[76:79], v[148:151], v[214:217], v[76:79]
	v_mfma_f32_16x16x32_bf16 v[72:75], v[156:159], v[214:217], v[72:75]
	v_mfma_f32_16x16x32_bf16 v[124:127], v[152:155], v[188:191], v[124:127]
	v_mfma_f32_16x16x32_bf16 v[120:123], v[160:163], v[188:191], v[120:123]
	v_mfma_f32_16x16x32_bf16 v[108:111], v[152:155], v[196:199], v[108:111]
	v_mfma_f32_16x16x32_bf16 v[104:107], v[160:163], v[196:199], v[104:107]
	v_mfma_f32_16x16x32_bf16 v[92:95], v[152:155], v[210:213], v[92:95]
	v_mfma_f32_16x16x32_bf16 v[88:91], v[160:163], v[210:213], v[88:91]
	v_mfma_f32_16x16x32_bf16 v[76:79], v[152:155], v[218:221], v[76:79]
	v_mfma_f32_16x16x32_bf16 v[72:75], v[160:163], v[218:221], v[72:75]
	v_mfma_f32_16x16x32_bf16 v[116:119], v[164:167], v[184:187], v[116:119]
	v_mfma_f32_16x16x32_bf16 v[112:115], v[176:179], v[184:187], v[112:115]
	v_mfma_f32_16x16x32_bf16 v[100:103], v[164:167], v[192:195], v[100:103]
	v_mfma_f32_16x16x32_bf16 v[96:99], v[176:179], v[192:195], v[96:99]
	v_mfma_f32_16x16x32_bf16 v[84:87], v[164:167], v[202:205], v[84:87]
	v_mfma_f32_16x16x32_bf16 v[80:83], v[176:179], v[202:205], v[80:83]
	v_mfma_f32_16x16x32_bf16 v[68:71], v[164:167], v[214:217], v[68:71]
	v_mfma_f32_16x16x32_bf16 v[64:67], v[176:179], v[214:217], v[64:67]
	v_mfma_f32_16x16x32_bf16 v[116:119], v[168:171], v[188:191], v[116:119]
	v_mfma_f32_16x16x32_bf16 v[112:115], v[180:183], v[188:191], v[112:115]
	v_mfma_f32_16x16x32_bf16 v[100:103], v[168:171], v[196:199], v[100:103]
	v_mfma_f32_16x16x32_bf16 v[96:99], v[180:183], v[196:199], v[96:99]
	v_mfma_f32_16x16x32_bf16 v[84:87], v[168:171], v[210:213], v[84:87]
	v_mfma_f32_16x16x32_bf16 v[80:83], v[180:183], v[210:213], v[80:83]
	v_mfma_f32_16x16x32_bf16 v[68:71], v[168:171], v[218:221], v[68:71]
	v_mfma_f32_16x16x32_bf16 v[64:67], v[180:183], v[218:221], v[64:67]
	s_barrier
; #define PG8_STAGE(bufoff, gbase, voff) do { _Pragma("unroll") for (int _i = 0; _i < 2; ++_i) \
;         __builtin_amdgcn_global_load_lds((const unsigned*)((const char*)(gbase) + (voff)[_i]), (PG8_LAS unsigned*)(lds + (bufoff) + ldsw + _i * 8192), 16, 0, 0); } while (0)
; #define PG8_STAGEA(bufoff, gbase, voff) do { _Pragma("unroll") for (int _i = 0; _i < 2; ++_i) \
;         __builtin_amdgcn_global_load_lds((const unsigned*)((const char*)(gbase) + (voff)[_i]), (PG8_LAS unsigned*)(lds + (bufoff) + ldsw + _i * 8192), 16, 0, AUXA); } while (0)
; #define PG8_LDA(dst, b, h) do { _Pragma("unroll") for (int m = 0; m < 4; ++m) _Pragma("unroll") for (int k = 0; k < 2; ++k) dst[m][k] = *(const PG8_LAS bf16x8*)(lds + PG8_SA(b, h) + aoff + m * 2048 + k * 1024); } while (0)
; #define PG8_LDB(dst, b, h) do { _Pragma("unroll") for (int n = 0; n < 2; ++n) _Pragma("unroll") for (int k = 0; k < 2; ++k) dst[n][k] = *(const PG8_LAS bf16x8*)(lds + PG8_SB(b, h) + boff + n * 2048 + k * 1024); } while (0)
; #define PG8_WAIT_V(n) asm volatile("s_waitcnt vmcnt(" #n ")" ::: "memory")
; #define PG8_WAIT_L(n) asm volatile("s_waitcnt lgkmcnt(" #n ")" ::: "memory")
; #define PG8_BAR __builtin_amdgcn_s_barrier()
; #define PG8_SCHED __builtin_amdgcn_sched_barrier(0)
;     ...
;             if constexpr (SP2) {
;             PG8_LDB(B0, 0, 0); PG8_LDB(B1, 0, 1); PG8_SCHED; PG8_LDA(At, 0, 0); PG8_STAGEA(PG8_SA(1, 1), a1 + hstep, voffA);
;             PG8_WAIT_V(8); PG8_WAIT_L(0); PG8_BAR; PG8_MMA(0, 0, At, B0); PG8_MMA(0, 1, At, B1); PG8_BAR; PG8_SCHED;
;             PG8_LDA(At, 0, 1); PG8_STAGE(PG8_SB(0, 0), b2, voffB); PG8_STAGE(PG8_SB(0, 1), b2 + hstepB, voffB); PG8_STAGEA(PG8_SA(0, 0), a2, voffA);
;             PG8_WAIT_V(8); PG8_WAIT_L(0); PG8_BAR; PG8_MMA(1, 0, At, B0); PG8_MMA(1, 1, At, B1); PG8_BAR; PG8_SCHED;
;             PG8_LDB(B0, 1, 0); PG8_LDB(B1, 1, 1); PG8_SCHED; PG8_LDA(At, 1, 0); PG8_STAGEA(PG8_SA(0, 1), a2 + hstep, voffA);
;             PG8_WAIT_V(8); PG8_WAIT_L(0); PG8_BAR; PG8_MMA(0, 0, At, B0); PG8_MMA(0, 1, At, B1); PG8_BAR; PG8_SCHED;
;             PG8_LDA(At, 1, 1); PG8_STAGE(PG8_SB(1, 0), b3, voffB); PG8_STAGE(PG8_SB(1, 1), b3 + hstepB, voffB); PG8_STAGEA(PG8_SA(1, 0), a3, voffA);
;             PG8_WAIT_V(8); PG8_WAIT_L(0); PG8_BAR; PG8_MMA(1, 0, At, B0); PG8_MMA(1, 1, At, B1); PG8_BAR; PG8_SCHED;
;     ...
;         if constexpr (ALIGN_EPI) { if (wr == 0) PG8_BAR; }
	s_mov_b32 m0, s29
	v_lshl_add_u64 v[172:173], v[172:173], 0, s[10:11]
	s_add_u32 s14, s14, 0x10080
	ds_read_b128 v[184:187], v144 offset:49152
	ds_read_b128 v[188:191], v144 offset:50176
	ds_read_b128 v[192:195], v144 offset:51200
	ds_read_b128 v[196:199], v144 offset:52224
	ds_read_b128 v[202:205], v144 offset:53248
	ds_read_b128 v[210:213], v144 offset:54272
	ds_read_b128 v[214:217], v144 offset:55296
	ds_read_b128 v[218:221], v144 offset:56320
	global_load_lds_dwordx4 v[172:173], off
	v_lshl_add_u64 v[172:173], v[206:207], 0, s[10:11]
	s_mov_b32 m0, s30
	s_addc_u32 s15, s15, 0
	global_load_lds_dwordx4 v[172:173], off
	v_lshl_add_u64 v[172:173], s[14:15], 0, v[134:135]
	s_mov_b32 m0, s31
	s_nop 0
	global_load_lds_dwordx4 v[172:173], off
	v_lshl_add_u64 v[172:173], s[14:15], 0, v[130:131]
	s_mov_b32 m0, s34
	s_nop 0
	global_load_lds_dwordx4 v[172:173], off
	v_lshl_add_u64 v[172:173], v[222:223], 0, s[10:11]
	s_mov_b32 m0, s20
	s_nop 0
	global_load_lds_dwordx4 v[172:173], off
	v_lshl_add_u64 v[172:173], v[224:225], 0, s[10:11]
	s_mov_b32 m0, s21
	s_nop 0
	global_load_lds_dwordx4 v[172:173], off
	s_waitcnt vmcnt(8)
	s_waitcnt lgkmcnt(0)
	s_barrier
	v_mfma_f32_16x16x32_bf16 v[60:63], v[148:151], v[184:187], v[60:63]
	v_mfma_f32_16x16x32_bf16 v[56:59], v[156:159], v[184:187], v[56:59]
	v_mfma_f32_16x16x32_bf16 v[44:47], v[148:151], v[192:195], v[44:47]
	s_add_i32 s22, s22, 2
	v_mfma_f32_16x16x32_bf16 v[40:43], v[156:159], v[192:195], v[40:43]
	v_mfma_f32_16x16x32_bf16 v[28:31], v[148:151], v[202:205], v[28:31]
	s_add_u32 s12, s12, 0x100
	v_mfma_f32_16x16x32_bf16 v[24:27], v[156:159], v[202:205], v[24:27]
	v_mfma_f32_16x16x32_bf16 v[12:15], v[148:151], v[214:217], v[12:15]
	s_addc_u32 s13, s13, 0
	v_mfma_f32_16x16x32_bf16 v[8:11], v[156:159], v[214:217], v[8:11]
	v_mfma_f32_16x16x32_bf16 v[60:63], v[152:155], v[188:191], v[60:63]
	v_mfma_f32_16x16x32_bf16 v[56:59], v[160:163], v[188:191], v[56:59]
	v_mfma_f32_16x16x32_bf16 v[44:47], v[152:155], v[196:199], v[44:47]
	v_mfma_f32_16x16x32_bf16 v[40:43], v[160:163], v[196:199], v[40:43]
	v_mfma_f32_16x16x32_bf16 v[28:31], v[152:155], v[210:213], v[28:31]
	v_mfma_f32_16x16x32_bf16 v[24:27], v[160:163], v[210:213], v[24:27]
	v_mfma_f32_16x16x32_bf16 v[12:15], v[152:155], v[218:221], v[12:15]
	v_mfma_f32_16x16x32_bf16 v[8:11], v[160:163], v[218:221], v[8:11]
	v_mfma_f32_16x16x32_bf16 v[52:55], v[164:167], v[184:187], v[52:55]
	v_mfma_f32_16x16x32_bf16 v[48:51], v[176:179], v[184:187], v[48:51]
	v_mfma_f32_16x16x32_bf16 v[36:39], v[164:167], v[192:195], v[36:39]
	v_mfma_f32_16x16x32_bf16 v[32:35], v[176:179], v[192:195], v[32:35]
	v_mfma_f32_16x16x32_bf16 v[20:23], v[164:167], v[202:205], v[20:23]
	v_mfma_f32_16x16x32_bf16 v[16:19], v[176:179], v[202:205], v[16:19]
	v_mfma_f32_16x16x32_bf16 v[4:7], v[164:167], v[214:217], v[4:7]
	v_mfma_f32_16x16x32_bf16 v[0:3], v[176:179], v[214:217], v[0:3]
	v_mfma_f32_16x16x32_bf16 v[52:55], v[168:171], v[188:191], v[52:55]
	v_mfma_f32_16x16x32_bf16 v[48:51], v[180:183], v[188:191], v[48:51]
	v_mfma_f32_16x16x32_bf16 v[36:39], v[168:171], v[196:199], v[36:39]
	v_mfma_f32_16x16x32_bf16 v[32:35], v[180:183], v[196:199], v[32:35]
	v_mfma_f32_16x16x32_bf16 v[20:23], v[168:171], v[210:213], v[20:23]
	v_mfma_f32_16x16x32_bf16 v[16:19], v[180:183], v[210:213], v[16:19]
	v_mfma_f32_16x16x32_bf16 v[4:7], v[168:171], v[218:221], v[4:7]
	v_mfma_f32_16x16x32_bf16 v[0:3], v[180:183], v[218:221], v[0:3]
	s_barrier
	s_cmp_gt_u32 s22, 13
	s_cbranch_scc0 .LBB0_758
	s_setprio 0
	v_readlane_b32 s1, v255, 10
	s_cmpk_lt_u32 s1, 0x100
	s_cbranch_scc0 .LBB0_761
	s_barrier

; #define PG8_STAGE(bufoff, gbase, voff) do { _Pragma("unroll") for (int _i = 0; _i < 2; ++_i) \
;         __builtin_amdgcn_global_load_lds((const unsigned*)((const char*)(gbase) + (voff)[_i]), (PG8_LAS unsigned*)(lds + (bufoff) + ldsw + _i * 8192), 16, 0, 0); } while (0)
; #define PG8_STAGEA(bufoff, gbase, voff) do { _Pragma("unroll") for (int _i = 0; _i < 2; ++_i) \
;         __builtin_amdgcn_global_load_lds((const unsigned*)((const char*)(gbase) + (voff)[_i]), (PG8_LAS unsigned*)(lds + (bufoff) + ldsw + _i * 8192), 16, 0, AUXA); } while (0)
; #define PG8_LDA(dst, b, h) do { _Pragma("unroll") for (int m = 0; m < 4; ++m) _Pragma("unroll") for (int k = 0; k < 2; ++k) dst[m][k] = *(const PG8_LAS bf16x8*)(lds + PG8_SA(b, h) + aoff + m * 2048 + k * 1024); } while (0)
; #define PG8_LDB(dst, b, h) do { _Pragma("unroll") for (int n = 0; n < 2; ++n) _Pragma("unroll") for (int k = 0; k < 2; ++k) dst[n][k] = *(const PG8_LAS bf16x8*)(lds + PG8_SB(b, h) + boff + n * 2048 + k * 1024); } while (0)
; #define PG8_WAIT_V(n) asm volatile("s_waitcnt vmcnt(" #n ")" ::: "memory")
; #define PG8_WAIT_L(n) asm volatile("s_waitcnt lgkmcnt(" #n ")" ::: "memory")
; #define PG8_BAR __builtin_amdgcn_s_barrier()
; #define PG8_SCHED __builtin_amdgcn_sched_barrier(0)
;     ...
;             if constexpr (SP2) {
;             PG8_LDB(B0, 0, 0); PG8_LDB(B1, 0, 1); PG8_SCHED; PG8_LDA(At, 0, 0); PG8_STAGEA(PG8_SA(1, 1), a1 + hstep, voffA);
;             PG8_WAIT_V(8); PG8_WAIT_L(0); PG8_BAR; PG8_MMA(0, 0, At, B0); PG8_MMA(0, 1, At, B1); PG8_BAR; PG8_SCHED;
;             PG8_LDA(At, 0, 1); PG8_STAGE(PG8_SB(0, 0), b2, voffB); PG8_STAGE(PG8_SB(0, 1), b2 + hstepB, voffB); PG8_STAGEA(PG8_SA(0, 0), a2, voffA);
;             PG8_WAIT_V(8); PG8_WAIT_L(0); PG8_BAR; PG8_MMA(1, 0, At, B0); PG8_MMA(1, 1, At, B1); PG8_BAR; PG8_SCHED;
;             PG8_LDB(B0, 1, 0); PG8_LDB(B1, 1, 1); PG8_SCHED; PG8_LDA(At, 1, 0); PG8_STAGEA(PG8_SA(0, 1), a2 + hstep, voffA);
;             PG8_WAIT_V(8); PG8_WAIT_L(0); PG8_BAR; PG8_MMA(0, 0, At, B0); PG8_MMA(0, 1, At, B1); PG8_BAR; PG8_SCHED;
;             PG8_LDA(At, 1, 1); PG8_STAGE(PG8_SB(1, 0), b3, voffB); PG8_STAGE(PG8_SB(1, 1), b3 + hstepB, voffB); PG8_STAGEA(PG8_SA(1, 0), a3, voffA);
;             PG8_WAIT_V(8); PG8_WAIT_L(0); PG8_BAR; PG8_MMA(1, 0, At, B0); PG8_MMA(1, 1, At, B1); PG8_BAR; PG8_SCHED;
.Lsp5_back:
	v_lshl_add_u64 v[206:207], v[142:143], 0, s[36:37]
	s_add_i32 m0, s17, 0xc000
	ds_read_b128 v[184:187], v149
	ds_read_b128 v[188:191], v149 offset:1024
	ds_read_b128 v[192:195], v149 offset:2048
	ds_read_b128 v[196:199], v149 offset:3072
	ds_read_b128 v[202:205], v149 offset:4096
	ds_read_b128 v[210:213], v149 offset:5120
	ds_read_b128 v[214:217], v149 offset:6144
	ds_read_b128 v[218:221], v149 offset:7168
	global_load_lds_dwordx4 v[206:207], off
	v_lshl_add_u64 v[206:207], v[144:145], 0, s[36:37]
	s_add_i32 m0, s17, 0xe000
	s_nop 0
	global_load_lds_dwordx4 v[206:207], off
	s_waitcnt vmcnt(8)
	s_waitcnt lgkmcnt(0)
	s_barrier
	v_mfma_f32_16x16x32_bf16 v[124:127], v[150:153], v[184:187], v[124:127]
	v_mfma_f32_16x16x32_bf16 v[120:123], v[158:161], v[184:187], v[120:123]
	v_mfma_f32_16x16x32_bf16 v[108:111], v[150:153], v[192:195], v[108:111]
	v_mfma_f32_16x16x32_bf16 v[104:107], v[158:161], v[192:195], v[104:107]
	v_mfma_f32_16x16x32_bf16 v[92:95], v[150:153], v[202:205], v[92:95]
	v_mfma_f32_16x16x32_bf16 v[88:91], v[158:161], v[202:205], v[88:91]
	v_mfma_f32_16x16x32_bf16 v[76:79], v[150:153], v[214:217], v[76:79]
	v_mfma_f32_16x16x32_bf16 v[72:75], v[158:161], v[214:217], v[72:75]
	v_mfma_f32_16x16x32_bf16 v[124:127], v[154:157], v[188:191], v[124:127]
	v_mfma_f32_16x16x32_bf16 v[120:123], v[162:165], v[188:191], v[120:123]
	v_mfma_f32_16x16x32_bf16 v[108:111], v[154:157], v[196:199], v[108:111]
	v_mfma_f32_16x16x32_bf16 v[104:107], v[162:165], v[196:199], v[104:107]
	v_mfma_f32_16x16x32_bf16 v[92:95], v[154:157], v[210:213], v[92:95]
	v_mfma_f32_16x16x32_bf16 v[88:91], v[162:165], v[210:213], v[88:91]
	v_mfma_f32_16x16x32_bf16 v[76:79], v[154:157], v[218:221], v[76:79]
	v_mfma_f32_16x16x32_bf16 v[72:75], v[162:165], v[218:221], v[72:75]
	v_mfma_f32_16x16x32_bf16 v[116:119], v[166:169], v[184:187], v[116:119]
	v_mfma_f32_16x16x32_bf16 v[112:115], v[176:179], v[184:187], v[112:115]
	v_mfma_f32_16x16x32_bf16 v[100:103], v[166:169], v[192:195], v[100:103]
	v_mfma_f32_16x16x32_bf16 v[96:99], v[176:179], v[192:195], v[96:99]
	v_mfma_f32_16x16x32_bf16 v[84:87], v[166:169], v[202:205], v[84:87]
	v_mfma_f32_16x16x32_bf16 v[80:83], v[176:179], v[202:205], v[80:83]
	v_mfma_f32_16x16x32_bf16 v[68:71], v[166:169], v[214:217], v[68:71]
	v_mfma_f32_16x16x32_bf16 v[64:67], v[176:179], v[214:217], v[64:67]
	v_mfma_f32_16x16x32_bf16 v[116:119], v[170:173], v[188:191], v[116:119]
	v_mfma_f32_16x16x32_bf16 v[112:115], v[180:183], v[188:191], v[112:115]
	v_mfma_f32_16x16x32_bf16 v[100:103], v[170:173], v[196:199], v[100:103]
	v_mfma_f32_16x16x32_bf16 v[96:99], v[180:183], v[196:199], v[96:99]
	v_mfma_f32_16x16x32_bf16 v[84:87], v[170:173], v[210:213], v[84:87]
	v_mfma_f32_16x16x32_bf16 v[80:83], v[180:183], v[210:213], v[80:83]
	v_mfma_f32_16x16x32_bf16 v[68:71], v[170:173], v[218:221], v[68:71]
	v_mfma_f32_16x16x32_bf16 v[64:67], v[180:183], v[218:221], v[64:67]
	s_barrier
	s_add_i32 s59, s12, s67
	v_lshl_add_u64 v[206:207], s[38:39], 0, v[132:133]
	s_mov_b32 m0, s59
	ds_read_b128 v[184:187], v149 offset:16384
	ds_read_b128 v[188:191], v149 offset:17408
	ds_read_b128 v[192:195], v149 offset:18432
	ds_read_b128 v[196:199], v149 offset:19456
	ds_read_b128 v[202:205], v149 offset:20480
	ds_read_b128 v[210:213], v149 offset:21504
	ds_read_b128 v[214:217], v149 offset:22528
	ds_read_b128 v[218:221], v149 offset:23552
	global_load_lds_dwordx4 v[206:207], off
	s_add_i32 m0, s59, 0x2000
	s_add_u32 s70, s38, 0x10000
	v_lshl_add_u64 v[222:223], s[38:39], 0, v[128:129]
	s_addc_u32 s71, s39, 0
	s_add_i32 s59, s50, s67
	global_load_lds_dwordx4 v[222:223], off
	v_lshl_add_u64 v[224:225], s[70:71], 0, v[132:133]
	s_mov_b32 m0, s59
	v_lshl_add_u64 v[226:227], s[40:41], 0, v[130:131]
	global_load_lds_dwordx4 v[224:225], off
	v_lshl_add_u64 v[224:225], s[70:71], 0, v[128:129]
	s_add_i32 m0, s59, 0x2000
	s_nop 0
	global_load_lds_dwordx4 v[224:225], off
	v_lshl_add_u64 v[224:225], s[40:41], 0, v[134:135]
	s_mov_b32 m0, s17
	s_nop 0
	global_load_lds_dwordx4 v[224:225], off
	s_mov_b32 m0, s43
	s_nop 0
	global_load_lds_dwordx4 v[226:227], off
	s_waitcnt vmcnt(8)
	s_waitcnt lgkmcnt(0)
	s_barrier
	v_mfma_f32_16x16x32_bf16 v[60:63], v[150:153], v[184:187], v[60:63]
	v_mfma_f32_16x16x32_bf16 v[56:59], v[158:161], v[184:187], v[56:59]
	v_mfma_f32_16x16x32_bf16 v[44:47], v[150:153], v[192:195], v[44:47]
	v_mfma_f32_16x16x32_bf16 v[40:43], v[158:161], v[192:195], v[40:43]
	v_mfma_f32_16x16x32_bf16 v[28:31], v[150:153], v[202:205], v[28:31]
	v_mfma_f32_16x16x32_bf16 v[24:27], v[158:161], v[202:205], v[24:27]
	v_mfma_f32_16x16x32_bf16 v[12:15], v[150:153], v[214:217], v[12:15]
	v_mfma_f32_16x16x32_bf16 v[8:11], v[158:161], v[214:217], v[8:11]
	v_mfma_f32_16x16x32_bf16 v[60:63], v[154:157], v[188:191], v[60:63]
	v_mfma_f32_16x16x32_bf16 v[56:59], v[162:165], v[188:191], v[56:59]
	v_mfma_f32_16x16x32_bf16 v[44:47], v[154:157], v[196:199], v[44:47]
	v_mfma_f32_16x16x32_bf16 v[40:43], v[162:165], v[196:199], v[40:43]
	v_mfma_f32_16x16x32_bf16 v[28:31], v[154:157], v[210:213], v[28:31]
	v_mfma_f32_16x16x32_bf16 v[24:27], v[162:165], v[210:213], v[24:27]
	v_mfma_f32_16x16x32_bf16 v[12:15], v[154:157], v[218:221], v[12:15]
	v_mfma_f32_16x16x32_bf16 v[8:11], v[162:165], v[218:221], v[8:11]
	v_mfma_f32_16x16x32_bf16 v[52:55], v[166:169], v[184:187], v[52:55]
	v_mfma_f32_16x16x32_bf16 v[48:51], v[176:179], v[184:187], v[48:51]
	v_mfma_f32_16x16x32_bf16 v[36:39], v[166:169], v[192:195], v[36:39]
	v_mfma_f32_16x16x32_bf16 v[32:35], v[176:179], v[192:195], v[32:35]
	v_mfma_f32_16x16x32_bf16 v[20:23], v[166:169], v[202:205], v[20:23]
	v_mfma_f32_16x16x32_bf16 v[16:19], v[176:179], v[202:205], v[16:19]
	v_mfma_f32_16x16x32_bf16 v[4:7], v[166:169], v[214:217], v[4:7]
	v_mfma_f32_16x16x32_bf16 v[0:3], v[176:179], v[214:217], v[0:3]
	v_mfma_f32_16x16x32_bf16 v[52:55], v[170:173], v[188:191], v[52:55]
	v_mfma_f32_16x16x32_bf16 v[48:51], v[180:183], v[188:191], v[48:51]
	v_mfma_f32_16x16x32_bf16 v[36:39], v[170:173], v[196:199], v[36:39]
	v_mfma_f32_16x16x32_bf16 v[32:35], v[180:183], v[196:199], v[32:35]
	v_mfma_f32_16x16x32_bf16 v[20:23], v[170:173], v[210:213], v[20:23]
	v_mfma_f32_16x16x32_bf16 v[16:19], v[180:183], v[210:213], v[16:19]
	v_mfma_f32_16x16x32_bf16 v[4:7], v[170:173], v[218:221], v[4:7]
	v_mfma_f32_16x16x32_bf16 v[0:3], v[180:183], v[218:221], v[0:3]
	s_barrier
; #define PG8_STAGE(bufoff, gbase, voff) do { _Pragma("unroll") for (int _i = 0; _i < 2; ++_i) \
;         __builtin_amdgcn_global_load_lds((const unsigned*)((const char*)(gbase) + (voff)[_i]), (PG8_LAS unsigned*)(lds + (bufoff) + ldsw + _i * 8192), 16, 0, 0); } while (0)
; #define PG8_STAGEA(bufoff, gbase, voff) do { _Pragma("unroll") for (int _i = 0; _i < 2; ++_i) \
;         __builtin_amdgcn_global_load_lds((const unsigned*)((const char*)(gbase) + (voff)[_i]), (PG8_LAS unsigned*)(lds + (bufoff) + ldsw + _i * 8192), 16, 0, AUXA); } while (0)
; #define PG8_LDA(dst, b, h) do { _Pragma("unroll") for (int m = 0; m < 4; ++m) _Pragma("unroll") for (int k = 0; k < 2; ++k) dst[m][k] = *(const PG8_LAS bf16x8*)(lds + PG8_SA(b, h) + aoff + m * 2048 + k * 1024); } while (0)
; #define PG8_LDB(dst, b, h) do { _Pragma("unroll") for (int n = 0; n < 2; ++n) _Pragma("unroll") for (int k = 0; k < 2; ++k) dst[n][k] = *(const PG8_LAS bf16x8*)(lds + PG8_SB(b, h) + boff + n * 2048 + k * 1024); } while (0)
; #define PG8_WAIT_V(n) asm volatile("s_waitcnt vmcnt(" #n ")" ::: "memory")
; #define PG8_WAIT_L(n) asm volatile("s_waitcnt lgkmcnt(" #n ")" ::: "memory")
; #define PG8_BAR __builtin_amdgcn_s_barrier()
; #define PG8_SCHED __builtin_amdgcn_sched_barrier(0)
;     ...
;             if constexpr (SP2) {
;             PG8_LDB(B0, 0, 0); PG8_LDB(B1, 0, 1); PG8_SCHED; PG8_LDA(At, 0, 0); PG8_STAGEA(PG8_SA(1, 1), a1 + hstep, voffA);
;             PG8_WAIT_V(8); PG8_WAIT_L(0); PG8_BAR; PG8_MMA(0, 0, At, B0); PG8_MMA(0, 1, At, B1); PG8_BAR; PG8_SCHED;
;             PG8_LDA(At, 0, 1); PG8_STAGE(PG8_SB(0, 0), b2, voffB); PG8_STAGE(PG8_SB(0, 1), b2 + hstepB, voffB); PG8_STAGEA(PG8_SA(0, 0), a2, voffA);
;             PG8_WAIT_V(8); PG8_WAIT_L(0); PG8_BAR; PG8_MMA(1, 0, At, B0); PG8_MMA(1, 1, At, B1); PG8_BAR; PG8_SCHED;
;             PG8_LDB(B0, 1, 0); PG8_LDB(B1, 1, 1); PG8_SCHED; PG8_LDA(At, 1, 0); PG8_STAGEA(PG8_SA(0, 1), a2 + hstep, voffA);
;             PG8_WAIT_V(8); PG8_WAIT_L(0); PG8_BAR; PG8_MMA(0, 0, At, B0); PG8_MMA(0, 1, At, B1); PG8_BAR; PG8_SCHED;
;             PG8_LDA(At, 1, 1); PG8_STAGE(PG8_SB(1, 0), b3, voffB); PG8_STAGE(PG8_SB(1, 1), b3 + hstepB, voffB); PG8_STAGEA(PG8_SA(1, 0), a3, voffA);
;             PG8_WAIT_V(8); PG8_WAIT_L(0); PG8_BAR; PG8_MMA(1, 0, At, B0); PG8_MMA(1, 1, At, B1); PG8_BAR; PG8_SCHED;
;     ...
;         if constexpr (ALIGN_EPI) { if (wr == 0) PG8_BAR; }
	s_add_i32 s59, 0, 0x18000
	s_add_i32 s70, 0, 0x1c000
	v_add_u32_e32 v162, s59, v148
	v_add_u32_e32 v174, s70, v148
	ds_read_b128 v[150:153], v162
	ds_read_b128 v[154:157], v162 offset:1024
	ds_read_b128 v[158:161], v162 offset:2048
	ds_read_b128 v[162:165], v162 offset:3072
	ds_read_b128 v[166:169], v174
	ds_read_b128 v[170:173], v174 offset:1024
	ds_read_b128 v[176:179], v174 offset:2048
	ds_read_b128 v[180:183], v174 offset:3072
	s_add_u32 s40, s40, 0x40000
	s_addc_u32 s41, s41, 0
	s_mov_b32 m0, s44
	v_lshl_add_u64 v[228:229], s[40:41], 0, v[134:135]
	ds_read_b128 v[184:187], v149 offset:32768
	ds_read_b128 v[188:191], v149 offset:33792
	ds_read_b128 v[192:195], v149 offset:34816
	ds_read_b128 v[196:199], v149 offset:35840
	ds_read_b128 v[202:205], v149 offset:36864
	ds_read_b128 v[210:213], v149 offset:37888
	ds_read_b128 v[214:217], v149 offset:38912
	ds_read_b128 v[218:221], v149 offset:39936
	global_load_lds_dwordx4 v[228:229], off
	v_lshl_add_u64 v[228:229], s[40:41], 0, v[130:131]
	s_mov_b32 m0, s45
	s_nop 0
	global_load_lds_dwordx4 v[228:229], off
	s_waitcnt vmcnt(8)
	s_waitcnt lgkmcnt(0)
	s_barrier
	v_mfma_f32_16x16x32_bf16 v[124:127], v[150:153], v[184:187], v[124:127]
	v_mfma_f32_16x16x32_bf16 v[120:123], v[158:161], v[184:187], v[120:123]
	v_mfma_f32_16x16x32_bf16 v[108:111], v[150:153], v[192:195], v[108:111]
	v_mfma_f32_16x16x32_bf16 v[104:107], v[158:161], v[192:195], v[104:107]
	v_mfma_f32_16x16x32_bf16 v[92:95], v[150:153], v[202:205], v[92:95]
	v_mfma_f32_16x16x32_bf16 v[88:91], v[158:161], v[202:205], v[88:91]
	v_mfma_f32_16x16x32_bf16 v[76:79], v[150:153], v[214:217], v[76:79]
	v_mfma_f32_16x16x32_bf16 v[72:75], v[158:161], v[214:217], v[72:75]
	v_mfma_f32_16x16x32_bf16 v[124:127], v[154:157], v[188:191], v[124:127]
	v_mfma_f32_16x16x32_bf16 v[120:123], v[162:165], v[188:191], v[120:123]
	v_mfma_f32_16x16x32_bf16 v[108:111], v[154:157], v[196:199], v[108:111]
	v_mfma_f32_16x16x32_bf16 v[104:107], v[162:165], v[196:199], v[104:107]
	v_mfma_f32_16x16x32_bf16 v[92:95], v[154:157], v[210:213], v[92:95]
	v_mfma_f32_16x16x32_bf16 v[88:91], v[162:165], v[210:213], v[88:91]
	v_mfma_f32_16x16x32_bf16 v[76:79], v[154:157], v[218:221], v[76:79]
	v_mfma_f32_16x16x32_bf16 v[72:75], v[162:165], v[218:221], v[72:75]
	v_mfma_f32_16x16x32_bf16 v[116:119], v[166:169], v[184:187], v[116:119]
	v_mfma_f32_16x16x32_bf16 v[112:115], v[176:179], v[184:187], v[112:115]
	v_mfma_f32_16x16x32_bf16 v[100:103], v[166:169], v[192:195], v[100:103]
	v_mfma_f32_16x16x32_bf16 v[96:99], v[176:179], v[192:195], v[96:99]
	v_mfma_f32_16x16x32_bf16 v[84:87], v[166:169], v[202:205], v[84:87]
	v_mfma_f32_16x16x32_bf16 v[80:83], v[176:179], v[202:205], v[80:83]
	v_mfma_f32_16x16x32_bf16 v[68:71], v[166:169], v[214:217], v[68:71]
	v_mfma_f32_16x16x32_bf16 v[64:67], v[176:179], v[214:217], v[64:67]
	v_mfma_f32_16x16x32_bf16 v[116:119], v[170:173], v[188:191], v[116:119]
	v_mfma_f32_16x16x32_bf16 v[112:115], v[180:183], v[188:191], v[112:115]
	v_mfma_f32_16x16x32_bf16 v[100:103], v[170:173], v[196:199], v[100:103]
	v_mfma_f32_16x16x32_bf16 v[96:99], v[180:183], v[196:199], v[96:99]
	v_mfma_f32_16x16x32_bf16 v[84:87], v[170:173], v[210:213], v[84:87]
	v_mfma_f32_16x16x32_bf16 v[80:83], v[180:183], v[210:213], v[80:83]
	v_mfma_f32_16x16x32_bf16 v[68:71], v[170:173], v[218:221], v[68:71]
	v_mfma_f32_16x16x32_bf16 v[64:67], v[180:183], v[218:221], v[64:67]
	s_barrier
	s_add_i32 s40, s59, s67
	v_lshl_add_u64 v[206:207], v[206:207], 0, s[20:21]
	s_mov_b32 m0, s40
	ds_read_b128 v[184:187], v149 offset:49152
	ds_read_b128 v[188:191], v149 offset:50176
	ds_read_b128 v[192:195], v149 offset:51200
	ds_read_b128 v[196:199], v149 offset:52224
	ds_read_b128 v[202:205], v149 offset:53248
	ds_read_b128 v[210:213], v149 offset:54272
	ds_read_b128 v[214:217], v149 offset:55296
	ds_read_b128 v[218:221], v149 offset:56320
	global_load_lds_dwordx4 v[206:207], off
	s_add_i32 m0, s40, 0x2000
	s_add_u32 s38, s38, 0x10080
	v_lshl_add_u64 v[206:207], v[222:223], 0, s[20:21]
	s_addc_u32 s39, s39, 0
	s_add_i32 s40, s70, s67
	global_load_lds_dwordx4 v[206:207], off
	v_lshl_add_u64 v[206:207], s[38:39], 0, v[132:133]
	s_mov_b32 m0, s40
	s_nop 0
	global_load_lds_dwordx4 v[206:207], off
	v_lshl_add_u64 v[206:207], s[38:39], 0, v[128:129]
	s_add_i32 m0, s40, 0x2000
	s_nop 0
	global_load_lds_dwordx4 v[206:207], off
	v_lshl_add_u64 v[206:207], v[224:225], 0, s[20:21]
	s_mov_b32 m0, s46
	s_nop 0
	global_load_lds_dwordx4 v[206:207], off
	v_lshl_add_u64 v[206:207], v[226:227], 0, s[20:21]
	s_mov_b32 m0, s47
	s_nop 0
	global_load_lds_dwordx4 v[206:207], off
	s_waitcnt vmcnt(8)
	s_waitcnt lgkmcnt(0)
	s_barrier
	v_mfma_f32_16x16x32_bf16 v[60:63], v[150:153], v[184:187], v[60:63]
	v_mfma_f32_16x16x32_bf16 v[56:59], v[158:161], v[184:187], v[56:59]
	v_mfma_f32_16x16x32_bf16 v[44:47], v[150:153], v[192:195], v[44:47]
	s_add_i32 s58, s58, 2
	v_mfma_f32_16x16x32_bf16 v[40:43], v[158:161], v[192:195], v[40:43]
	v_mfma_f32_16x16x32_bf16 v[28:31], v[150:153], v[202:205], v[28:31]
	s_add_u32 s36, s36, 0x100
	v_mfma_f32_16x16x32_bf16 v[24:27], v[158:161], v[202:205], v[24:27]
	v_mfma_f32_16x16x32_bf16 v[12:15], v[150:153], v[214:217], v[12:15]
	s_addc_u32 s37, s37, 0
	v_mfma_f32_16x16x32_bf16 v[8:11], v[158:161], v[214:217], v[8:11]
	v_mfma_f32_16x16x32_bf16 v[60:63], v[154:157], v[188:191], v[60:63]
	v_mfma_f32_16x16x32_bf16 v[56:59], v[162:165], v[188:191], v[56:59]
	v_mfma_f32_16x16x32_bf16 v[44:47], v[154:157], v[196:199], v[44:47]
	v_mfma_f32_16x16x32_bf16 v[40:43], v[162:165], v[196:199], v[40:43]
	v_mfma_f32_16x16x32_bf16 v[28:31], v[154:157], v[210:213], v[28:31]
	v_mfma_f32_16x16x32_bf16 v[24:27], v[162:165], v[210:213], v[24:27]
	v_mfma_f32_16x16x32_bf16 v[12:15], v[154:157], v[218:221], v[12:15]
	v_mfma_f32_16x16x32_bf16 v[8:11], v[162:165], v[218:221], v[8:11]
	v_mfma_f32_16x16x32_bf16 v[52:55], v[166:169], v[184:187], v[52:55]
	v_mfma_f32_16x16x32_bf16 v[48:51], v[176:179], v[184:187], v[48:51]
	v_mfma_f32_16x16x32_bf16 v[36:39], v[166:169], v[192:195], v[36:39]
	v_mfma_f32_16x16x32_bf16 v[32:35], v[176:179], v[192:195], v[32:35]
	v_mfma_f32_16x16x32_bf16 v[20:23], v[166:169], v[202:205], v[20:23]
	v_mfma_f32_16x16x32_bf16 v[16:19], v[176:179], v[202:205], v[16:19]
	v_mfma_f32_16x16x32_bf16 v[4:7], v[166:169], v[214:217], v[4:7]
	v_mfma_f32_16x16x32_bf16 v[0:3], v[176:179], v[214:217], v[0:3]
	v_mfma_f32_16x16x32_bf16 v[52:55], v[170:173], v[188:191], v[52:55]
	v_mfma_f32_16x16x32_bf16 v[48:51], v[180:183], v[188:191], v[48:51]
	v_mfma_f32_16x16x32_bf16 v[36:39], v[170:173], v[196:199], v[36:39]
	v_mfma_f32_16x16x32_bf16 v[32:35], v[180:183], v[196:199], v[32:35]
	v_mfma_f32_16x16x32_bf16 v[20:23], v[170:173], v[210:213], v[20:23]
	v_mfma_f32_16x16x32_bf16 v[16:19], v[180:183], v[210:213], v[16:19]
	v_mfma_f32_16x16x32_bf16 v[4:7], v[170:173], v[218:221], v[4:7]
	v_mfma_f32_16x16x32_bf16 v[0:3], v[180:183], v[218:221], v[0:3]
	s_barrier
	s_cmp_gt_u32 s58, 13
	s_cbranch_scc0 .LBB0_888
	s_setprio 0
	s_and_b64 vcc, exec, s[22:23]
	s_cbranch_vccz .LBB0_891
	s_barrier

; #define PG8_STAGE(bufoff, gbase, voff) do { _Pragma("unroll") for (int _i = 0; _i < 2; ++_i) \
;         __builtin_amdgcn_global_load_lds((const unsigned*)((const char*)(gbase) + (voff)[_i]), (PG8_LAS unsigned*)(lds + (bufoff) + ldsw + _i * 8192), 16, 0, 0); } while (0)
; #define PG8_STAGEA(bufoff, gbase, voff) do { _Pragma("unroll") for (int _i = 0; _i < 2; ++_i) \
;         __builtin_amdgcn_global_load_lds((const unsigned*)((const char*)(gbase) + (voff)[_i]), (PG8_LAS unsigned*)(lds + (bufoff) + ldsw + _i * 8192), 16, 0, AUXA); } while (0)
; #define PG8_LDA(dst, b, h) do { _Pragma("unroll") for (int m = 0; m < 4; ++m) _Pragma("unroll") for (int k = 0; k < 2; ++k) dst[m][k] = *(const PG8_LAS bf16x8*)(lds + PG8_SA(b, h) + aoff + m * 2048 + k * 1024); } while (0)
; #define PG8_LDB(dst, b, h) do { _Pragma("unroll") for (int n = 0; n < 2; ++n) _Pragma("unroll") for (int k = 0; k < 2; ++k) dst[n][k] = *(const PG8_LAS bf16x8*)(lds + PG8_SB(b, h) + boff + n * 2048 + k * 1024); } while (0)
; #define PG8_WAIT_V(n) asm volatile("s_waitcnt vmcnt(" #n ")" ::: "memory")
; #define PG8_WAIT_L(n) asm volatile("s_waitcnt lgkmcnt(" #n ")" ::: "memory")
; #define PG8_BAR __builtin_amdgcn_s_barrier()
; #define PG8_SCHED __builtin_amdgcn_sched_barrier(0)
;     ...
;             if constexpr (SP2) {
;             PG8_LDB(B0, 0, 0); PG8_LDB(B1, 0, 1); PG8_SCHED; PG8_LDA(At, 0, 0); PG8_STAGEA(PG8_SA(1, 1), a1 + hstep, voffA);
;             PG8_WAIT_V(8); PG8_WAIT_L(0); PG8_BAR; PG8_MMA(0, 0, At, B0); PG8_MMA(0, 1, At, B1); PG8_BAR; PG8_SCHED;
;             PG8_LDA(At, 0, 1); PG8_STAGE(PG8_SB(0, 0), b2, voffB); PG8_STAGE(PG8_SB(0, 1), b2 + hstepB, voffB); PG8_STAGEA(PG8_SA(0, 0), a2, voffA);
;             PG8_WAIT_V(8); PG8_WAIT_L(0); PG8_BAR; PG8_MMA(1, 0, At, B0); PG8_MMA(1, 1, At, B1); PG8_BAR; PG8_SCHED;
;             PG8_LDB(B0, 1, 0); PG8_LDB(B1, 1, 1); PG8_SCHED; PG8_LDA(At, 1, 0); PG8_STAGEA(PG8_SA(0, 1), a2 + hstep, voffA);
;             PG8_WAIT_V(8); PG8_WAIT_L(0); PG8_BAR; PG8_MMA(0, 0, At, B0); PG8_MMA(0, 1, At, B1); PG8_BAR; PG8_SCHED;
;             PG8_LDA(At, 1, 1); PG8_STAGE(PG8_SB(1, 0), b3, voffB); PG8_STAGE(PG8_SB(1, 1), b3 + hstepB, voffB); PG8_STAGEA(PG8_SA(1, 0), a3, voffA);
;             PG8_WAIT_V(8); PG8_WAIT_L(0); PG8_BAR; PG8_MMA(1, 0, At, B0); PG8_MMA(1, 1, At, B1); PG8_BAR; PG8_SCHED;
.Lfiw_p6_0:
	s_waitcnt lgkmcnt(0)
	s_barrier
	v_mfma_f32_16x16x32_bf16 v[60:63], v[144:147], v[184:187], v[60:63]
	v_mfma_f32_16x16x32_bf16 v[56:59], v[152:155], v[184:187], v[56:59]
	v_mfma_f32_16x16x32_bf16 v[44:47], v[144:147], v[192:195], v[44:47]
	v_mfma_f32_16x16x32_bf16 v[40:43], v[152:155], v[192:195], v[40:43]
	v_mfma_f32_16x16x32_bf16 v[28:31], v[144:147], v[202:205], v[28:31]
	v_mfma_f32_16x16x32_bf16 v[24:27], v[152:155], v[202:205], v[24:27]
	v_mfma_f32_16x16x32_bf16 v[12:15], v[144:147], v[214:217], v[12:15]
	v_mfma_f32_16x16x32_bf16 v[8:11], v[152:155], v[214:217], v[8:11]
	v_mfma_f32_16x16x32_bf16 v[60:63], v[148:151], v[188:191], v[60:63]
	v_mfma_f32_16x16x32_bf16 v[56:59], v[156:159], v[188:191], v[56:59]
	v_mfma_f32_16x16x32_bf16 v[44:47], v[148:151], v[196:199], v[44:47]
	v_mfma_f32_16x16x32_bf16 v[40:43], v[156:159], v[196:199], v[40:43]
	v_mfma_f32_16x16x32_bf16 v[28:31], v[148:151], v[210:213], v[28:31]
	v_mfma_f32_16x16x32_bf16 v[24:27], v[156:159], v[210:213], v[24:27]
	v_mfma_f32_16x16x32_bf16 v[12:15], v[148:151], v[218:221], v[12:15]
	v_mfma_f32_16x16x32_bf16 v[8:11], v[156:159], v[218:221], v[8:11]
	v_mfma_f32_16x16x32_bf16 v[52:55], v[160:163], v[184:187], v[52:55]
	v_mfma_f32_16x16x32_bf16 v[48:51], v[176:179], v[184:187], v[48:51]
	v_mfma_f32_16x16x32_bf16 v[36:39], v[160:163], v[192:195], v[36:39]
	v_mfma_f32_16x16x32_bf16 v[32:35], v[176:179], v[192:195], v[32:35]
	v_mfma_f32_16x16x32_bf16 v[20:23], v[160:163], v[202:205], v[20:23]
	v_mfma_f32_16x16x32_bf16 v[16:19], v[176:179], v[202:205], v[16:19]
	v_mfma_f32_16x16x32_bf16 v[4:7], v[160:163], v[214:217], v[4:7]
	v_mfma_f32_16x16x32_bf16 v[0:3], v[176:179], v[214:217], v[0:3]
	v_mfma_f32_16x16x32_bf16 v[52:55], v[164:167], v[188:191], v[52:55]
	v_mfma_f32_16x16x32_bf16 v[48:51], v[180:183], v[188:191], v[48:51]
	v_mfma_f32_16x16x32_bf16 v[36:39], v[164:167], v[196:199], v[36:39]
	v_mfma_f32_16x16x32_bf16 v[32:35], v[180:183], v[196:199], v[32:35]
	v_mfma_f32_16x16x32_bf16 v[20:23], v[164:167], v[210:213], v[20:23]
	v_mfma_f32_16x16x32_bf16 v[16:19], v[180:183], v[210:213], v[16:19]
	v_mfma_f32_16x16x32_bf16 v[4:7], v[164:167], v[218:221], v[4:7]
	v_mfma_f32_16x16x32_bf16 v[0:3], v[180:183], v[218:221], v[0:3]
	s_barrier
	s_add_i32 s73, 0, 0x18000
	s_add_i32 s74, 0, 0x1c000
	v_add_u32_e32 v156, s73, v169
	v_add_u32_e32 v173, s74, v169
	ds_read_b128 v[144:147], v156
	ds_read_b128 v[148:151], v156 offset:1024
	ds_read_b128 v[152:155], v156 offset:2048
	ds_read_b128 v[156:159], v156 offset:3072
	ds_read_b128 v[160:163], v173
	ds_read_b128 v[164:167], v173 offset:1024
	ds_read_b128 v[176:179], v173 offset:2048
	ds_read_b128 v[180:183], v173 offset:3072
	s_add_u32 s42, s42, 0x40000
	s_addc_u32 s43, s43, 0
	s_mov_b32 m0, s47
	v_lshl_add_u64 v[228:229], s[42:43], 0, v[134:135]
	ds_read_b128 v[184:187], v172 offset:32768
	ds_read_b128 v[188:191], v172 offset:33792
	ds_read_b128 v[192:195], v172 offset:34816
	ds_read_b128 v[196:199], v172 offset:35840
	ds_read_b128 v[202:205], v172 offset:36864
	ds_read_b128 v[210:213], v172 offset:37888
	ds_read_b128 v[214:217], v172 offset:38912
	ds_read_b128 v[218:221], v172 offset:39936
	global_load_lds_dwordx4 v[228:229], off
	v_lshl_add_u64 v[228:229], s[42:43], 0, v[130:131]
	s_mov_b32 m0, s50
	s_nop 0
	global_load_lds_dwordx4 v[228:229], off
	s_mov_b32 s99, 0
	s_waitcnt vmcnt(8)
	s_waitcnt lgkmcnt(0)
	s_barrier
	v_mfma_f32_16x16x32_bf16 v[124:127], v[144:147], v[184:187], v[124:127]
	v_mfma_f32_16x16x32_bf16 v[120:123], v[152:155], v[184:187], v[120:123]
	v_mfma_f32_16x16x32_bf16 v[108:111], v[144:147], v[192:195], v[108:111]
	v_mfma_f32_16x16x32_bf16 v[104:107], v[152:155], v[192:195], v[104:107]
	v_mfma_f32_16x16x32_bf16 v[92:95], v[144:147], v[202:205], v[92:95]
	v_mfma_f32_16x16x32_bf16 v[88:91], v[152:155], v[202:205], v[88:91]
	v_mfma_f32_16x16x32_bf16 v[76:79], v[144:147], v[214:217], v[76:79]
	v_mfma_f32_16x16x32_bf16 v[72:75], v[152:155], v[214:217], v[72:75]
	v_mfma_f32_16x16x32_bf16 v[124:127], v[148:151], v[188:191], v[124:127]
	v_mfma_f32_16x16x32_bf16 v[120:123], v[156:159], v[188:191], v[120:123]
	v_mfma_f32_16x16x32_bf16 v[108:111], v[148:151], v[196:199], v[108:111]
	v_mfma_f32_16x16x32_bf16 v[104:107], v[156:159], v[196:199], v[104:107]
	v_mfma_f32_16x16x32_bf16 v[92:95], v[148:151], v[210:213], v[92:95]
	v_mfma_f32_16x16x32_bf16 v[88:91], v[156:159], v[210:213], v[88:91]
	v_mfma_f32_16x16x32_bf16 v[76:79], v[148:151], v[218:221], v[76:79]
	v_mfma_f32_16x16x32_bf16 v[72:75], v[156:159], v[218:221], v[72:75]
	v_mfma_f32_16x16x32_bf16 v[116:119], v[160:163], v[184:187], v[116:119]
	v_mfma_f32_16x16x32_bf16 v[112:115], v[176:179], v[184:187], v[112:115]
	v_mfma_f32_16x16x32_bf16 v[100:103], v[160:163], v[192:195], v[100:103]
	v_mfma_f32_16x16x32_bf16 v[96:99], v[176:179], v[192:195], v[96:99]
	v_mfma_f32_16x16x32_bf16 v[84:87], v[160:163], v[202:205], v[84:87]
	v_mfma_f32_16x16x32_bf16 v[80:83], v[176:179], v[202:205], v[80:83]
	v_mfma_f32_16x16x32_bf16 v[68:71], v[160:163], v[214:217], v[68:71]
	v_mfma_f32_16x16x32_bf16 v[64:67], v[176:179], v[214:217], v[64:67]
	v_mfma_f32_16x16x32_bf16 v[116:119], v[164:167], v[188:191], v[116:119]
	v_mfma_f32_16x16x32_bf16 v[112:115], v[180:183], v[188:191], v[112:115]
	v_mfma_f32_16x16x32_bf16 v[100:103], v[164:167], v[196:199], v[100:103]
	v_mfma_f32_16x16x32_bf16 v[96:99], v[180:183], v[196:199], v[96:99]
	v_mfma_f32_16x16x32_bf16 v[84:87], v[164:167], v[210:213], v[84:87]
	v_mfma_f32_16x16x32_bf16 v[80:83], v[180:183], v[210:213], v[80:83]
	v_mfma_f32_16x16x32_bf16 v[68:71], v[164:167], v[218:221], v[68:71]
	v_mfma_f32_16x16x32_bf16 v[64:67], v[180:183], v[218:221], v[64:67]
	s_barrier
; #define PG8_STAGE(bufoff, gbase, voff) do { _Pragma("unroll") for (int _i = 0; _i < 2; ++_i) \
;         __builtin_amdgcn_global_load_lds((const unsigned*)((const char*)(gbase) + (voff)[_i]), (PG8_LAS unsigned*)(lds + (bufoff) + ldsw + _i * 8192), 16, 0, 0); } while (0)
; #define PG8_STAGEA(bufoff, gbase, voff) do { _Pragma("unroll") for (int _i = 0; _i < 2; ++_i) \
;         __builtin_amdgcn_global_load_lds((const unsigned*)((const char*)(gbase) + (voff)[_i]), (PG8_LAS unsigned*)(lds + (bufoff) + ldsw + _i * 8192), 16, 0, AUXA); } while (0)
; #define PG8_LDA(dst, b, h) do { _Pragma("unroll") for (int m = 0; m < 4; ++m) _Pragma("unroll") for (int k = 0; k < 2; ++k) dst[m][k] = *(const PG8_LAS bf16x8*)(lds + PG8_SA(b, h) + aoff + m * 2048 + k * 1024); } while (0)
; #define PG8_MMA(ai, bj, At, Bt) do { __builtin_amdgcn_s_setprio(1); _Pragma("unroll") for (int m = 0; m < 4; ++m) _Pragma("unroll") for (int n = 0; n < 2; ++n) _Pragma("unroll") for (int k = 0; k < 2; ++k) \
;         acc[ai][bj][m][n] = __builtin_amdgcn_mfma_f32_16x16x32_bf16(Bt[n][k], At[m][k], acc[ai][bj][m][n], 0, 0, 0); __builtin_amdgcn_s_setprio(0); } while (0)
; #define PG8_WAIT_V(n) asm volatile("s_waitcnt vmcnt(" #n ")" ::: "memory")
; #define PG8_WAIT_L(n) asm volatile("s_waitcnt lgkmcnt(" #n ")" ::: "memory")
; #define PG8_BAR __builtin_amdgcn_s_barrier()
; #define PG8_SCHED __builtin_amdgcn_sched_barrier(0)
;     ...
;         for (int t = 0; t < nt; t += 2) {
;             const bool last = (t == nt - 2);
;             const char* a1 = cA + (size_t)(t + 1) * kstep;
;             const char* a2 = last ? nA : cA + (size_t)(t + 2) * kstep; const char* b2 = last ? nB : cB + (size_t)(t + 2) * kstep;
;             const char* a3 = a2 + kstep; const char* b3 = b2 + kstep;
;     ...
;             PG8_LDA(At, 1, 1); PG8_STAGE(PG8_SB(1, 0), b3, voffB); PG8_STAGE(PG8_SB(1, 1), b3 + hstepB, voffB); PG8_STAGEA(PG8_SA(1, 0), a3, voffA);
;             PG8_WAIT_V(8); PG8_WAIT_L(0); PG8_BAR; PG8_MMA(1, 0, At, B0); PG8_MMA(1, 1, At, B1); PG8_BAR; PG8_SCHED;
	s_add_i32 s42, s73, s67
	v_lshl_add_u64 v[206:207], v[206:207], 0, s[16:17]
	s_mov_b32 m0, s42
	ds_read_b128 v[184:187], v172 offset:49152
	ds_read_b128 v[188:191], v172 offset:50176
	ds_read_b128 v[192:195], v172 offset:51200
	ds_read_b128 v[196:199], v172 offset:52224
	ds_read_b128 v[202:205], v172 offset:53248
	ds_read_b128 v[210:213], v172 offset:54272
	ds_read_b128 v[214:217], v172 offset:55296
	ds_read_b128 v[218:221], v172 offset:56320
	global_load_lds_dwordx4 v[206:207], off
	s_add_i32 m0, s42, 0x2000
	s_add_u32 s40, s40, 0x10080
	v_lshl_add_u64 v[206:207], v[222:223], 0, s[16:17]
	s_addc_u32 s41, s41, 0
	s_add_i32 s42, s74, s67
	global_load_lds_dwordx4 v[206:207], off
	v_lshl_add_u64 v[206:207], s[40:41], 0, v[132:133]
	s_mov_b32 m0, s42
	s_nop 0
	global_load_lds_dwordx4 v[206:207], off
	v_lshl_add_u64 v[206:207], s[40:41], 0, v[128:129]
	s_add_i32 m0, s42, 0x2000
	s_nop 0
	global_load_lds_dwordx4 v[206:207], off
	v_lshl_add_u64 v[206:207], v[224:225], 0, s[16:17]
	s_mov_b32 m0, s51
	s_nop 0
	global_load_lds_dwordx4 v[206:207], off
	v_lshl_add_u64 v[206:207], v[226:227], 0, s[16:17]
	s_mov_b32 m0, s52
	s_nop 0
	global_load_lds_dwordx4 v[206:207], off
	s_waitcnt vmcnt(8)
	s_waitcnt lgkmcnt(0)
	s_barrier
	v_mfma_f32_16x16x32_bf16 v[60:63], v[144:147], v[184:187], v[60:63]
	v_mfma_f32_16x16x32_bf16 v[56:59], v[152:155], v[184:187], v[56:59]
	v_mfma_f32_16x16x32_bf16 v[44:47], v[144:147], v[192:195], v[44:47]
	s_add_i32 s71, s71, 2
	v_mfma_f32_16x16x32_bf16 v[40:43], v[152:155], v[192:195], v[40:43]
	v_mfma_f32_16x16x32_bf16 v[28:31], v[144:147], v[202:205], v[28:31]
	s_add_u32 s38, s38, 0x100
	v_mfma_f32_16x16x32_bf16 v[24:27], v[152:155], v[202:205], v[24:27]
	v_mfma_f32_16x16x32_bf16 v[12:15], v[144:147], v[214:217], v[12:15]
	s_addc_u32 s39, s39, 0
	v_mfma_f32_16x16x32_bf16 v[8:11], v[152:155], v[214:217], v[8:11]
	v_mfma_f32_16x16x32_bf16 v[60:63], v[148:151], v[188:191], v[60:63]
	s_add_u32 s59, s59, 0x100
	v_mfma_f32_16x16x32_bf16 v[56:59], v[156:159], v[188:191], v[56:59]
	v_mfma_f32_16x16x32_bf16 v[44:47], v[148:151], v[196:199], v[44:47]
	s_addc_u32 s70, s70, 0
	v_mfma_f32_16x16x32_bf16 v[40:43], v[156:159], v[196:199], v[40:43]
	v_mfma_f32_16x16x32_bf16 v[28:31], v[148:151], v[210:213], v[28:31]
	v_mfma_f32_16x16x32_bf16 v[24:27], v[156:159], v[210:213], v[24:27]
	v_mfma_f32_16x16x32_bf16 v[12:15], v[148:151], v[218:221], v[12:15]
	v_mfma_f32_16x16x32_bf16 v[8:11], v[156:159], v[218:221], v[8:11]
	v_mfma_f32_16x16x32_bf16 v[52:55], v[160:163], v[184:187], v[52:55]
	v_mfma_f32_16x16x32_bf16 v[48:51], v[176:179], v[184:187], v[48:51]
	v_mfma_f32_16x16x32_bf16 v[36:39], v[160:163], v[192:195], v[36:39]
	v_mfma_f32_16x16x32_bf16 v[32:35], v[176:179], v[192:195], v[32:35]
	v_mfma_f32_16x16x32_bf16 v[20:23], v[160:163], v[202:205], v[20:23]
	v_mfma_f32_16x16x32_bf16 v[16:19], v[176:179], v[202:205], v[16:19]
	v_mfma_f32_16x16x32_bf16 v[4:7], v[160:163], v[214:217], v[4:7]
	v_mfma_f32_16x16x32_bf16 v[0:3], v[176:179], v[214:217], v[0:3]
	v_mfma_f32_16x16x32_bf16 v[52:55], v[164:167], v[188:191], v[52:55]
	v_mfma_f32_16x16x32_bf16 v[48:51], v[180:183], v[188:191], v[48:51]
	v_mfma_f32_16x16x32_bf16 v[36:39], v[164:167], v[196:199], v[36:39]
	v_mfma_f32_16x16x32_bf16 v[32:35], v[180:183], v[196:199], v[32:35]
	v_mfma_f32_16x16x32_bf16 v[20:23], v[164:167], v[210:213], v[20:23]
	v_mfma_f32_16x16x32_bf16 v[16:19], v[180:183], v[210:213], v[16:19]
	v_mfma_f32_16x16x32_bf16 v[4:7], v[164:167], v[218:221], v[4:7]
	v_mfma_f32_16x16x32_bf16 v[0:3], v[180:183], v[218:221], v[0:3]
	s_barrier
	s_cmp_gt_u32 s71, 13
	s_cbranch_scc0 .LBB0_977
	s_setprio 0
	s_and_b64 vcc, exec, s[18:19]
	s_cbranch_vccz .LBB0_980
	s_barrier

; #define PG8_STAGE(bufoff, gbase, voff) do { _Pragma("unroll") for (int _i = 0; _i < 2; ++_i) \
;         __builtin_amdgcn_global_load_lds((const unsigned*)((const char*)(gbase) + (voff)[_i]), (PG8_LAS unsigned*)(lds + (bufoff) + ldsw + _i * 8192), 16, 0, 0); } while (0)
; #define PG8_STAGEA(bufoff, gbase, voff) do { _Pragma("unroll") for (int _i = 0; _i < 2; ++_i) \
;         __builtin_amdgcn_global_load_lds((const unsigned*)((const char*)(gbase) + (voff)[_i]), (PG8_LAS unsigned*)(lds + (bufoff) + ldsw + _i * 8192), 16, 0, AUXA); } while (0)
; #define PG8_LDA(dst, b, h) do { _Pragma("unroll") for (int m = 0; m < 4; ++m) _Pragma("unroll") for (int k = 0; k < 2; ++k) dst[m][k] = *(const PG8_LAS bf16x8*)(lds + PG8_SA(b, h) + aoff + m * 2048 + k * 1024); } while (0)
; #define PG8_LDB(dst, b, h) do { _Pragma("unroll") for (int n = 0; n < 2; ++n) _Pragma("unroll") for (int k = 0; k < 2; ++k) dst[n][k] = *(const PG8_LAS bf16x8*)(lds + PG8_SB(b, h) + boff + n * 2048 + k * 1024); } while (0)
; #define PG8_MMA(ai, bj, At, Bt) do { __builtin_amdgcn_s_setprio(1); _Pragma("unroll") for (int m = 0; m < 4; ++m) _Pragma("unroll") for (int n = 0; n < 2; ++n) _Pragma("unroll") for (int k = 0; k < 2; ++k) \
;         acc[ai][bj][m][n] = __builtin_amdgcn_mfma_f32_16x16x32_bf16(Bt[n][k], At[m][k], acc[ai][bj][m][n], 0, 0, 0); __builtin_amdgcn_s_setprio(0); } while (0)
; #define PG8_WAIT_V(n) asm volatile("s_waitcnt vmcnt(" #n ")" ::: "memory")
; #define PG8_WAIT_L(n) asm volatile("s_waitcnt lgkmcnt(" #n ")" ::: "memory")
; #define PG8_BAR __builtin_amdgcn_s_barrier()
; #define PG8_SCHED __builtin_amdgcn_sched_barrier(0)
;     ...
;             PG8_LDB(B0, 0, 0); PG8_LDB(B1, 0, 1); PG8_SCHED; PG8_LDA(At, 0, 0); PG8_STAGEA(PG8_SA(1, 1), a1 + hstep, voffA);
;             PG8_WAIT_V(8); PG8_WAIT_L(0); PG8_BAR; PG8_MMA(0, 0, At, B0); PG8_MMA(0, 1, At, B1); PG8_BAR; PG8_SCHED;
;             PG8_LDA(At, 0, 1); PG8_STAGE(PG8_SB(0, 0), b2, voffB); PG8_STAGE(PG8_SB(0, 1), b2 + hstepB, voffB); PG8_STAGEA(PG8_SA(0, 0), a2, voffA);
;             PG8_WAIT_V(8); PG8_WAIT_L(0); PG8_BAR; PG8_MMA(1, 0, At, B0); PG8_MMA(1, 1, At, B1); PG8_BAR; PG8_SCHED;
.Lsp7_back:
	v_lshl_add_u64 v[206:207], s[38:39], 0, v[150:151]
	s_add_i32 m0, s49, 0xc000
	ds_read_b128 v[202:205], v164
	ds_read_b128 v[210:213], v164 offset:1024
	ds_read_b128 v[214:217], v164 offset:2048
	ds_read_b128 v[218:221], v164 offset:3072
	ds_read_b128 v[222:225], v164 offset:4096
	ds_read_b128 v[226:229], v164 offset:5120
	ds_read_b128 v[230:233], v164 offset:6144
	ds_read_b128 v[234:237], v164 offset:7168
	global_load_lds_dwordx4 v[206:207], off
	v_lshl_add_u64 v[206:207], s[38:39], 0, v[130:131]
	s_add_i32 m0, s49, 0xe000
	s_nop 0
	global_load_lds_dwordx4 v[206:207], off
	s_waitcnt vmcnt(8)
	s_waitcnt lgkmcnt(0)
	s_barrier
	v_mfma_f32_16x16x32_bf16 v[124:127], v[166:169], v[202:205], v[124:127]
	v_mfma_f32_16x16x32_bf16 v[120:123], v[176:179], v[202:205], v[120:123]
	v_mfma_f32_16x16x32_bf16 v[108:111], v[166:169], v[214:217], v[108:111]
	v_mfma_f32_16x16x32_bf16 v[104:107], v[176:179], v[214:217], v[104:107]
	v_mfma_f32_16x16x32_bf16 v[92:95], v[166:169], v[222:225], v[92:95]
	v_mfma_f32_16x16x32_bf16 v[88:91], v[176:179], v[222:225], v[88:91]
	v_mfma_f32_16x16x32_bf16 v[76:79], v[166:169], v[230:233], v[76:79]
	v_mfma_f32_16x16x32_bf16 v[72:75], v[176:179], v[230:233], v[72:75]
	v_mfma_f32_16x16x32_bf16 v[124:127], v[170:173], v[210:213], v[124:127]
	v_mfma_f32_16x16x32_bf16 v[120:123], v[180:183], v[210:213], v[120:123]
	v_mfma_f32_16x16x32_bf16 v[108:111], v[170:173], v[218:221], v[108:111]
	v_mfma_f32_16x16x32_bf16 v[104:107], v[180:183], v[218:221], v[104:107]
	v_mfma_f32_16x16x32_bf16 v[92:95], v[170:173], v[226:229], v[92:95]
	v_mfma_f32_16x16x32_bf16 v[88:91], v[180:183], v[226:229], v[88:91]
	v_mfma_f32_16x16x32_bf16 v[76:79], v[170:173], v[234:237], v[76:79]
	v_mfma_f32_16x16x32_bf16 v[72:75], v[180:183], v[234:237], v[72:75]
	v_mfma_f32_16x16x32_bf16 v[116:119], v[184:187], v[202:205], v[116:119]
	v_mfma_f32_16x16x32_bf16 v[112:115], v[192:195], v[202:205], v[112:115]
	v_mfma_f32_16x16x32_bf16 v[100:103], v[184:187], v[214:217], v[100:103]
	v_mfma_f32_16x16x32_bf16 v[96:99], v[192:195], v[214:217], v[96:99]
	v_mfma_f32_16x16x32_bf16 v[84:87], v[184:187], v[222:225], v[84:87]
	v_mfma_f32_16x16x32_bf16 v[80:83], v[192:195], v[222:225], v[80:83]
	v_mfma_f32_16x16x32_bf16 v[68:71], v[184:187], v[230:233], v[68:71]
	v_mfma_f32_16x16x32_bf16 v[64:67], v[192:195], v[230:233], v[64:67]
	v_mfma_f32_16x16x32_bf16 v[116:119], v[188:191], v[210:213], v[116:119]
	v_mfma_f32_16x16x32_bf16 v[112:115], v[196:199], v[210:213], v[112:115]
	v_mfma_f32_16x16x32_bf16 v[100:103], v[188:191], v[218:221], v[100:103]
	v_mfma_f32_16x16x32_bf16 v[96:99], v[196:199], v[218:221], v[96:99]
	v_mfma_f32_16x16x32_bf16 v[84:87], v[188:191], v[226:229], v[84:87]
	v_mfma_f32_16x16x32_bf16 v[80:83], v[196:199], v[226:229], v[80:83]
	v_mfma_f32_16x16x32_bf16 v[68:71], v[188:191], v[234:237], v[68:71]
	v_mfma_f32_16x16x32_bf16 v[64:67], v[196:199], v[234:237], v[64:67]
	s_barrier
	s_add_i32 s74, s59, s67
	v_lshl_add_u64 v[206:207], s[44:45], 0, v[136:137]
	s_mov_b32 m0, s74
	ds_read_b128 v[202:205], v164 offset:16384
	ds_read_b128 v[210:213], v164 offset:17408
	ds_read_b128 v[214:217], v164 offset:18432
	ds_read_b128 v[218:221], v164 offset:19456
	ds_read_b128 v[222:225], v164 offset:20480
	ds_read_b128 v[226:229], v164 offset:21504
	ds_read_b128 v[230:233], v164 offset:22528
	ds_read_b128 v[234:237], v164 offset:23552
	global_load_lds_dwordx4 v[206:207], off
	s_add_i32 m0, s74, 0x2000
	s_add_u32 s74, s44, 0x40000
	v_lshl_add_u64 v[238:239], s[44:45], 0, v[140:141]
	s_addc_u32 s75, s45, 0
	s_add_i32 s76, s70, s67
	global_load_lds_dwordx4 v[238:239], off
	v_lshl_add_u64 v[240:241], s[74:75], 0, v[136:137]
	s_mov_b32 m0, s76
	v_lshl_add_u64 v[242:243], s[50:51], 0, v[138:139]
	global_load_lds_dwordx4 v[240:241], off
	v_lshl_add_u64 v[240:241], s[74:75], 0, v[140:141]
	s_add_i32 m0, s76, 0x2000
	s_nop 0
	global_load_lds_dwordx4 v[240:241], off
	v_lshl_add_u64 v[240:241], s[50:51], 0, v[134:135]
	s_mov_b32 m0, s49
	s_nop 0
	global_load_lds_dwordx4 v[240:241], off
	s_mov_b32 m0, s52
	s_nop 0
	global_load_lds_dwordx4 v[242:243], off
	s_waitcnt vmcnt(8)
	s_waitcnt lgkmcnt(0)
	s_barrier
	v_mfma_f32_16x16x32_bf16 v[60:63], v[166:169], v[202:205], v[60:63]
	v_mfma_f32_16x16x32_bf16 v[56:59], v[176:179], v[202:205], v[56:59]
	v_mfma_f32_16x16x32_bf16 v[44:47], v[166:169], v[214:217], v[44:47]
	v_mfma_f32_16x16x32_bf16 v[40:43], v[176:179], v[214:217], v[40:43]
	v_mfma_f32_16x16x32_bf16 v[28:31], v[166:169], v[222:225], v[28:31]
	v_mfma_f32_16x16x32_bf16 v[24:27], v[176:179], v[222:225], v[24:27]
	v_mfma_f32_16x16x32_bf16 v[12:15], v[166:169], v[230:233], v[12:15]
	v_mfma_f32_16x16x32_bf16 v[8:11], v[176:179], v[230:233], v[8:11]
	v_mfma_f32_16x16x32_bf16 v[60:63], v[170:173], v[210:213], v[60:63]
	v_mfma_f32_16x16x32_bf16 v[56:59], v[180:183], v[210:213], v[56:59]
	v_mfma_f32_16x16x32_bf16 v[44:47], v[170:173], v[218:221], v[44:47]
	v_mfma_f32_16x16x32_bf16 v[40:43], v[180:183], v[218:221], v[40:43]
	v_mfma_f32_16x16x32_bf16 v[28:31], v[170:173], v[226:229], v[28:31]
	v_mfma_f32_16x16x32_bf16 v[24:27], v[180:183], v[226:229], v[24:27]
	v_mfma_f32_16x16x32_bf16 v[12:15], v[170:173], v[234:237], v[12:15]
	v_mfma_f32_16x16x32_bf16 v[8:11], v[180:183], v[234:237], v[8:11]
	v_mfma_f32_16x16x32_bf16 v[52:55], v[184:187], v[202:205], v[52:55]
	v_mfma_f32_16x16x32_bf16 v[48:51], v[192:195], v[202:205], v[48:51]
	v_mfma_f32_16x16x32_bf16 v[36:39], v[184:187], v[214:217], v[36:39]
	v_mfma_f32_16x16x32_bf16 v[32:35], v[192:195], v[214:217], v[32:35]
	v_mfma_f32_16x16x32_bf16 v[20:23], v[184:187], v[222:225], v[20:23]
	v_mfma_f32_16x16x32_bf16 v[16:19], v[192:195], v[222:225], v[16:19]
	v_mfma_f32_16x16x32_bf16 v[4:7], v[184:187], v[230:233], v[4:7]
	v_mfma_f32_16x16x32_bf16 v[0:3], v[192:195], v[230:233], v[0:3]
	v_mfma_f32_16x16x32_bf16 v[52:55], v[188:191], v[210:213], v[52:55]
	v_mfma_f32_16x16x32_bf16 v[48:51], v[196:199], v[210:213], v[48:51]
	v_mfma_f32_16x16x32_bf16 v[36:39], v[188:191], v[218:221], v[36:39]
	v_mfma_f32_16x16x32_bf16 v[32:35], v[196:199], v[218:221], v[32:35]
	v_mfma_f32_16x16x32_bf16 v[20:23], v[188:191], v[226:229], v[20:23]
	v_mfma_f32_16x16x32_bf16 v[16:19], v[196:199], v[226:229], v[16:19]
	v_mfma_f32_16x16x32_bf16 v[4:7], v[188:191], v[234:237], v[4:7]
	v_mfma_f32_16x16x32_bf16 v[0:3], v[196:199], v[234:237], v[0:3]
	s_barrier
; #define PG8_STAGEA(bufoff, gbase, voff) do { _Pragma("unroll") for (int _i = 0; _i < 2; ++_i) \
;         __builtin_amdgcn_global_load_lds((const unsigned*)((const char*)(gbase) + (voff)[_i]), (PG8_LAS unsigned*)(lds + (bufoff) + ldsw + _i * 8192), 16, 0, AUXA); } while (0)
; #define PG8_LDA(dst, b, h) do { _Pragma("unroll") for (int m = 0; m < 4; ++m) _Pragma("unroll") for (int k = 0; k < 2; ++k) dst[m][k] = *(const PG8_LAS bf16x8*)(lds + PG8_SA(b, h) + aoff + m * 2048 + k * 1024); } while (0)
; #define PG8_LDB(dst, b, h) do { _Pragma("unroll") for (int n = 0; n < 2; ++n) _Pragma("unroll") for (int k = 0; k < 2; ++k) dst[n][k] = *(const PG8_LAS bf16x8*)(lds + PG8_SB(b, h) + boff + n * 2048 + k * 1024); } while (0)
; #define PG8_MMA(ai, bj, At, Bt) do { __builtin_amdgcn_s_setprio(1); _Pragma("unroll") for (int m = 0; m < 4; ++m) _Pragma("unroll") for (int n = 0; n < 2; ++n) _Pragma("unroll") for (int k = 0; k < 2; ++k) \
;         acc[ai][bj][m][n] = __builtin_amdgcn_mfma_f32_16x16x32_bf16(Bt[n][k], At[m][k], acc[ai][bj][m][n], 0, 0, 0); __builtin_amdgcn_s_setprio(0); } while (0)
; #define PG8_WAIT_V(n) asm volatile("s_waitcnt vmcnt(" #n ")" ::: "memory")
; #define PG8_WAIT_L(n) asm volatile("s_waitcnt lgkmcnt(" #n ")" ::: "memory")
; #define PG8_BAR __builtin_amdgcn_s_barrier()
; #define PG8_SCHED __builtin_amdgcn_sched_barrier(0)
;     ...
;             PG8_LDB(B0, 1, 0); PG8_LDB(B1, 1, 1); PG8_SCHED; PG8_LDA(At, 1, 0); PG8_STAGEA(PG8_SA(0, 1), a2 + hstep, voffA);
;             PG8_WAIT_V(8); PG8_WAIT_L(0); PG8_BAR; PG8_MMA(0, 0, At, B0); PG8_MMA(0, 1, At, B1); PG8_BAR; PG8_SCHED;
	s_add_i32 s74, 0, 0x18000
	v_add_u32_e32 v128, s74, v163
	s_add_i32 s75, 0, 0x1c000
	ds_read_b128 v[166:169], v128
	ds_read_b128 v[170:173], v128 offset:1024
	ds_read_b128 v[176:179], v128 offset:2048
	ds_read_b128 v[180:183], v128 offset:3072
	v_add_u32_e32 v128, s75, v163
	ds_read_b128 v[184:187], v128
	ds_read_b128 v[188:191], v128 offset:1024
	ds_read_b128 v[192:195], v128 offset:2048
	ds_read_b128 v[196:199], v128 offset:3072
	s_add_u32 s50, s50, 0x100000
	s_addc_u32 s51, s51, 0
	s_mov_b32 m0, s53
	v_lshl_add_u64 v[244:245], s[50:51], 0, v[134:135]
	ds_read_b128 v[202:205], v164 offset:32768
	ds_read_b128 v[210:213], v164 offset:33792
	ds_read_b128 v[214:217], v164 offset:34816
	ds_read_b128 v[218:221], v164 offset:35840
	ds_read_b128 v[222:225], v164 offset:36864
	ds_read_b128 v[226:229], v164 offset:37888
	ds_read_b128 v[230:233], v164 offset:38912
	ds_read_b128 v[234:237], v164 offset:39936
	global_load_lds_dwordx4 v[244:245], off
	v_lshl_add_u64 v[244:245], s[50:51], 0, v[138:139]
	s_mov_b32 m0, s54
	s_nop 0
	global_load_lds_dwordx4 v[244:245], off
	s_waitcnt vmcnt(8)
	s_waitcnt lgkmcnt(0)
	s_barrier
	v_mfma_f32_16x16x32_bf16 v[124:127], v[166:169], v[202:205], v[124:127]
	v_mfma_f32_16x16x32_bf16 v[120:123], v[176:179], v[202:205], v[120:123]
	v_mfma_f32_16x16x32_bf16 v[108:111], v[166:169], v[214:217], v[108:111]
	v_mfma_f32_16x16x32_bf16 v[104:107], v[176:179], v[214:217], v[104:107]
	v_mfma_f32_16x16x32_bf16 v[92:95], v[166:169], v[222:225], v[92:95]
	v_mfma_f32_16x16x32_bf16 v[88:91], v[176:179], v[222:225], v[88:91]
	v_mfma_f32_16x16x32_bf16 v[76:79], v[166:169], v[230:233], v[76:79]
	v_mfma_f32_16x16x32_bf16 v[72:75], v[176:179], v[230:233], v[72:75]
	v_mfma_f32_16x16x32_bf16 v[124:127], v[170:173], v[210:213], v[124:127]
	v_mfma_f32_16x16x32_bf16 v[120:123], v[180:183], v[210:213], v[120:123]
	v_mfma_f32_16x16x32_bf16 v[108:111], v[170:173], v[218:221], v[108:111]
	v_mfma_f32_16x16x32_bf16 v[104:107], v[180:183], v[218:221], v[104:107]
	v_mfma_f32_16x16x32_bf16 v[92:95], v[170:173], v[226:229], v[92:95]
	v_mfma_f32_16x16x32_bf16 v[88:91], v[180:183], v[226:229], v[88:91]
	v_mfma_f32_16x16x32_bf16 v[76:79], v[170:173], v[234:237], v[76:79]
	v_mfma_f32_16x16x32_bf16 v[72:75], v[180:183], v[234:237], v[72:75]
	v_mfma_f32_16x16x32_bf16 v[116:119], v[184:187], v[202:205], v[116:119]
	v_mfma_f32_16x16x32_bf16 v[112:115], v[192:195], v[202:205], v[112:115]
	v_mfma_f32_16x16x32_bf16 v[100:103], v[184:187], v[214:217], v[100:103]
	v_mfma_f32_16x16x32_bf16 v[96:99], v[192:195], v[214:217], v[96:99]
	v_mfma_f32_16x16x32_bf16 v[84:87], v[184:187], v[222:225], v[84:87]
	v_mfma_f32_16x16x32_bf16 v[80:83], v[192:195], v[222:225], v[80:83]
	v_mfma_f32_16x16x32_bf16 v[68:71], v[184:187], v[230:233], v[68:71]
	v_mfma_f32_16x16x32_bf16 v[64:67], v[192:195], v[230:233], v[64:67]
	v_mfma_f32_16x16x32_bf16 v[116:119], v[188:191], v[210:213], v[116:119]
	v_mfma_f32_16x16x32_bf16 v[112:115], v[196:199], v[210:213], v[112:115]
	v_mfma_f32_16x16x32_bf16 v[100:103], v[188:191], v[218:221], v[100:103]
	v_mfma_f32_16x16x32_bf16 v[96:99], v[196:199], v[218:221], v[96:99]
	v_mfma_f32_16x16x32_bf16 v[84:87], v[188:191], v[226:229], v[84:87]
	v_mfma_f32_16x16x32_bf16 v[80:83], v[196:199], v[226:229], v[80:83]
	v_mfma_f32_16x16x32_bf16 v[68:71], v[188:191], v[234:237], v[68:71]
	v_mfma_f32_16x16x32_bf16 v[64:67], v[196:199], v[234:237], v[64:67]
	s_barrier
; #define PG8_STAGE(bufoff, gbase, voff) do { _Pragma("unroll") for (int _i = 0; _i < 2; ++_i) \
;         __builtin_amdgcn_global_load_lds((const unsigned*)((const char*)(gbase) + (voff)[_i]), (PG8_LAS unsigned*)(lds + (bufoff) + ldsw + _i * 8192), 16, 0, 0); } while (0)
; #define PG8_STAGEA(bufoff, gbase, voff) do { _Pragma("unroll") for (int _i = 0; _i < 2; ++_i) \
;         __builtin_amdgcn_global_load_lds((const unsigned*)((const char*)(gbase) + (voff)[_i]), (PG8_LAS unsigned*)(lds + (bufoff) + ldsw + _i * 8192), 16, 0, AUXA); } while (0)
; #define PG8_LDA(dst, b, h) do { _Pragma("unroll") for (int m = 0; m < 4; ++m) _Pragma("unroll") for (int k = 0; k < 2; ++k) dst[m][k] = *(const PG8_LAS bf16x8*)(lds + PG8_SA(b, h) + aoff + m * 2048 + k * 1024); } while (0)
; #define PG8_MMA(ai, bj, At, Bt) do { __builtin_amdgcn_s_setprio(1); _Pragma("unroll") for (int m = 0; m < 4; ++m) _Pragma("unroll") for (int n = 0; n < 2; ++n) _Pragma("unroll") for (int k = 0; k < 2; ++k) \
;         acc[ai][bj][m][n] = __builtin_amdgcn_mfma_f32_16x16x32_bf16(Bt[n][k], At[m][k], acc[ai][bj][m][n], 0, 0, 0); __builtin_amdgcn_s_setprio(0); } while (0)
; #define PG8_WAIT_V(n) asm volatile("s_waitcnt vmcnt(" #n ")" ::: "memory")
; #define PG8_WAIT_L(n) asm volatile("s_waitcnt lgkmcnt(" #n ")" ::: "memory")
; #define PG8_BAR __builtin_amdgcn_s_barrier()
; #define PG8_SCHED __builtin_amdgcn_sched_barrier(0)
;     ...
;         for (int t = 0; t < nt; t += 2) {
;             const bool last = (t == nt - 2);
;             const char* a1 = cA + (size_t)(t + 1) * kstep;
;             const char* a2 = last ? nA : cA + (size_t)(t + 2) * kstep; const char* b2 = last ? nB : cB + (size_t)(t + 2) * kstep;
;             const char* a3 = a2 + kstep; const char* b3 = b2 + kstep;
;     ...
;             PG8_LDA(At, 1, 1); PG8_STAGE(PG8_SB(1, 0), b3, voffB); PG8_STAGE(PG8_SB(1, 1), b3 + hstepB, voffB); PG8_STAGEA(PG8_SA(1, 0), a3, voffA);
;             PG8_WAIT_V(8); PG8_WAIT_L(0); PG8_BAR; PG8_MMA(1, 0, At, B0); PG8_MMA(1, 1, At, B1); PG8_BAR; PG8_SCHED;
	s_add_i32 s50, s74, s67
	v_lshl_add_u64 v[206:207], v[206:207], 0, s[16:17]
	s_mov_b32 m0, s50
	ds_read_b128 v[202:205], v164 offset:49152
	ds_read_b128 v[210:213], v164 offset:50176
	ds_read_b128 v[214:217], v164 offset:51200
	ds_read_b128 v[218:221], v164 offset:52224
	ds_read_b128 v[222:225], v164 offset:53248
	ds_read_b128 v[226:229], v164 offset:54272
	ds_read_b128 v[230:233], v164 offset:55296
	ds_read_b128 v[234:237], v164 offset:56320
	global_load_lds_dwordx4 v[206:207], off
	s_add_i32 m0, s50, 0x2000
	s_add_u32 s44, s44, 0x40080
	v_lshl_add_u64 v[206:207], v[238:239], 0, s[16:17]
	s_addc_u32 s45, s45, 0
	s_add_i32 s50, s75, s67
	global_load_lds_dwordx4 v[206:207], off
	v_lshl_add_u64 v[206:207], s[44:45], 0, v[136:137]
	s_mov_b32 m0, s50
	s_nop 0
	global_load_lds_dwordx4 v[206:207], off
	v_lshl_add_u64 v[206:207], s[44:45], 0, v[140:141]
	s_add_i32 m0, s50, 0x2000
	s_nop 0
	global_load_lds_dwordx4 v[206:207], off
	v_lshl_add_u64 v[206:207], v[240:241], 0, s[16:17]
	s_mov_b32 m0, s55
	s_nop 0
	global_load_lds_dwordx4 v[206:207], off
	v_lshl_add_u64 v[206:207], v[242:243], 0, s[16:17]
	s_mov_b32 m0, s56
	s_nop 0
	global_load_lds_dwordx4 v[206:207], off
	s_waitcnt vmcnt(8)
	s_waitcnt lgkmcnt(0)
	s_barrier
	v_mfma_f32_16x16x32_bf16 v[60:63], v[166:169], v[202:205], v[60:63]
	v_mfma_f32_16x16x32_bf16 v[56:59], v[176:179], v[202:205], v[56:59]
	v_mfma_f32_16x16x32_bf16 v[44:47], v[166:169], v[214:217], v[44:47]
	s_add_i32 s44, s73, 2
	v_mfma_f32_16x16x32_bf16 v[40:43], v[176:179], v[214:217], v[40:43]
	v_mfma_f32_16x16x32_bf16 v[28:31], v[166:169], v[222:225], v[28:31]
	s_add_u32 s42, s42, 0x100
	v_mfma_f32_16x16x32_bf16 v[24:27], v[176:179], v[222:225], v[24:27]
	v_mfma_f32_16x16x32_bf16 v[12:15], v[166:169], v[230:233], v[12:15]
	s_addc_u32 s43, s43, 0
	v_mfma_f32_16x16x32_bf16 v[8:11], v[176:179], v[230:233], v[8:11]
	v_mfma_f32_16x16x32_bf16 v[60:63], v[170:173], v[210:213], v[60:63]
	v_lshl_add_u64 v[150:151], v[150:151], 0, s[20:21]
	v_mfma_f32_16x16x32_bf16 v[56:59], v[180:183], v[210:213], v[56:59]
	v_mfma_f32_16x16x32_bf16 v[44:47], v[170:173], v[218:221], v[44:47]
	v_lshl_add_u64 v[130:131], v[130:131], 0, s[20:21]
	v_mfma_f32_16x16x32_bf16 v[40:43], v[180:183], v[218:221], v[40:43]
	v_mfma_f32_16x16x32_bf16 v[28:31], v[170:173], v[226:229], v[28:31]
	v_mfma_f32_16x16x32_bf16 v[24:27], v[180:183], v[226:229], v[24:27]
	v_mfma_f32_16x16x32_bf16 v[12:15], v[170:173], v[234:237], v[12:15]
	v_mfma_f32_16x16x32_bf16 v[8:11], v[180:183], v[234:237], v[8:11]
	v_mfma_f32_16x16x32_bf16 v[52:55], v[184:187], v[202:205], v[52:55]
	v_mfma_f32_16x16x32_bf16 v[48:51], v[192:195], v[202:205], v[48:51]
	v_mfma_f32_16x16x32_bf16 v[36:39], v[184:187], v[214:217], v[36:39]
	v_mfma_f32_16x16x32_bf16 v[32:35], v[192:195], v[214:217], v[32:35]
	v_mfma_f32_16x16x32_bf16 v[20:23], v[184:187], v[222:225], v[20:23]
	v_mfma_f32_16x16x32_bf16 v[16:19], v[192:195], v[222:225], v[16:19]
	v_mfma_f32_16x16x32_bf16 v[4:7], v[184:187], v[230:233], v[4:7]
	v_mfma_f32_16x16x32_bf16 v[0:3], v[192:195], v[230:233], v[0:3]
	v_mfma_f32_16x16x32_bf16 v[52:55], v[188:191], v[210:213], v[52:55]
	v_mfma_f32_16x16x32_bf16 v[48:51], v[196:199], v[210:213], v[48:51]
	v_mfma_f32_16x16x32_bf16 v[36:39], v[188:191], v[218:221], v[36:39]
	v_mfma_f32_16x16x32_bf16 v[32:35], v[196:199], v[218:221], v[32:35]
	v_mfma_f32_16x16x32_bf16 v[20:23], v[188:191], v[226:229], v[20:23]
	v_mfma_f32_16x16x32_bf16 v[16:19], v[196:199], v[226:229], v[16:19]
	v_mfma_f32_16x16x32_bf16 v[4:7], v[188:191], v[234:237], v[4:7]
	v_mfma_f32_16x16x32_bf16 v[0:3], v[196:199], v[234:237], v[0:3]
	s_barrier
	s_cmp_ge_i32 s73, s57
	s_mov_b32 s73, s44
	s_cbranch_scc0 .LBB0_1054
	s_setprio 0
	s_and_b64 vcc, exec, s[18:19]
	s_cbranch_vccz .LBB0_1057
	s_barrier
